# sample-item prologue: serialised gate, S_raw and q/k staging loads batched into three groups
# baseline (speedup 1.0000x reference)
.LBB0_817:
	s_lshl_b32 s6, s46, 1
	s_and_b32 s6, s6, -8
	v_mov_b32_e32 v36, v201
	v_mov_b32_e32 v2, 0
	s_addk_i32 s6, 0x4000
	s_ashr_i32 s47, s46, 31
	v_add_u32_e32 v38, s6, v2
	v_add_u32_e32 v0, s46, v2
	v_readlane_b32 s6, v255, 12
	v_ashrrev_i32_e32 v1, 31, v0
	v_readlane_b32 s7, v255, 13
	v_ashrrev_i32_e32 v39, 31, v38
	v_ashrrev_i32_e32 v3, 31, v2
	v_lshl_add_u64 v[0:1], v[0:1], 2, s[6:7]
	flat_load_dword v6, v[0:1]
	v_add_u32_e32 v0, s0, v2
	v_readlane_b32 s6, v255, 10
	v_ashrrev_i32_e32 v1, 31, v0
	v_readlane_b32 s7, v255, 11
	v_lshlrev_b64 v[40:41], 5, v[38:39]
	v_lshlrev_b64 v[2:3], 2, v[2:3]
	v_lshl_add_u64 v[4:5], v[0:1], 2, s[6:7]
	flat_load_dword v0, v[4:5]
	flat_load_dword v7, v[4:5] offset:16
	v_lshl_add_u64 v[4:5], s[34:35], 0, v[40:41]
	v_lshl_add_u64 v[4:5], v[4:5], 0, v[2:3]
	flat_load_dword v32, v[4:5]
	flat_load_dword v1, v[4:5] offset:16
	flat_load_dword v186, v[4:5] offset:32
	flat_load_dword v187, v[4:5] offset:48
	flat_load_dword v188, v[4:5] offset:64
	flat_load_dword v189, v[4:5] offset:80
	flat_load_dword v190, v[4:5] offset:96
	flat_load_dword v191, v[4:5] offset:112
	flat_load_dword v192, v[4:5] offset:128
	flat_load_dword v193, v[4:5] offset:144
	flat_load_dword v194, v[4:5] offset:160
	flat_load_dword v195, v[4:5] offset:176
	flat_load_dword v196, v[4:5] offset:192
	flat_load_dword v197, v[4:5] offset:208
	flat_load_dword v198, v[4:5] offset:224
	flat_load_dword v199, v[4:5] offset:240
	v_add_u32_e32 v46, 1, v38
	v_ashrrev_i32_e32 v47, 31, v46
	v_lshlrev_b64 v[42:43], 5, v[46:47]
	v_add_u32_e32 v50, 2, v38
	v_ashrrev_i32_e32 v51, 31, v50
	v_lshlrev_b64 v[48:49], 5, v[50:51]
	v_add_u32_e32 v56, 3, v38
	v_ashrrev_i32_e32 v57, 31, v56
	v_lshlrev_b64 v[54:55], 5, v[56:57]
	v_add_u32_e32 v62, 4, v38
	v_ashrrev_i32_e32 v63, 31, v62
	v_lshlrev_b64 v[60:61], 5, v[62:63]
	v_add_u32_e32 v70, 5, v38
	v_ashrrev_i32_e32 v71, 31, v70
	v_lshlrev_b64 v[64:65], 5, v[70:71]
	v_and_b32_e32 v90, 7, v36
	s_lshl_b64 s[6:7], s[46:47], 11
	s_add_u32 s48, s14, s6
	s_addc_u32 s49, s15, s7
	s_add_u32 s6, s8, s6
	s_addc_u32 s7, s9, s7
	s_waitcnt vmcnt(0) lgkmcnt(0)
	v_add_f32_e32 v1, v7, v1
	v_min_f32_e32 v20, 0, v1
	v_mul_f32_e64 v1, |v1|, s1
	v_exp_f32_e32 v1, v1
	s_nop 0
	v_add_f32_e32 v8, 1.0, v1
	v_add_f32_e32 v4, -1.0, v8
	v_sub_f32_e32 v5, v4, v8
	v_add_f32_e32 v5, 1.0, v5
	v_sub_f32_e32 v4, v1, v4
	v_add_f32_e32 v9, v4, v5
	v_frexp_mant_f32_e32 v4, v8
	v_cmp_gt_f32_e32 vcc, s4, v4
	v_cvt_f64_f32_e32 v[4:5], v8
	v_frexp_exp_i32_f64_e32 v4, v[4:5]
	v_subbrev_co_u32_e32 v14, vcc, 0, v4, vcc
	v_sub_u32_e32 v4, 0, v14
	v_ldexp_f32 v5, v8, v4
	v_add_f32_e32 v8, -1.0, v5
	v_add_f32_e32 v10, 1.0, v5
	v_ldexp_f32 v4, v9, v4
	v_add_f32_e32 v9, 1.0, v8
	v_add_f32_e32 v11, -1.0, v10
	v_sub_f32_e32 v9, v5, v9
	v_sub_f32_e32 v5, v5, v11
	v_add_f32_e32 v9, v4, v9
	v_add_f32_e32 v4, v4, v5
	v_add_f32_e32 v15, v10, v4
	v_rcp_f32_e32 v17, v15
	v_sub_f32_e32 v5, v15, v10
	v_sub_f32_e32 v16, v4, v5
	v_add_f32_e32 v5, v8, v9
	v_mul_f32_e32 v19, v5, v17
	v_sub_f32_e32 v4, v5, v8
	v_mul_f32_e32 v8, v15, v19
	v_fma_f32 v10, v19, v15, -v8
	v_fmac_f32_e32 v10, v19, v16
	v_sub_f32_e32 v18, v9, v4
	v_add_f32_e32 v4, v8, v10
	v_sub_f32_e32 v9, v5, v4
	v_pk_add_f32 v[12:13], v[4:5], v[8:9] neg_lo:[0,1] neg_hi:[0,1]
	v_mov_b32_e32 v11, v4
	v_pk_add_f32 v[4:5], v[12:13], v[10:11] neg_lo:[0,1] neg_hi:[0,1]
	v_cmp_neq_f32_e32 vcc, s45, v1
	v_add_f32_e32 v5, v18, v5
	v_add_f32_e32 v4, v4, v5
	v_add_f32_e32 v5, v9, v4
	v_mul_f32_e32 v18, v17, v5
	v_mul_f32_e32 v8, v15, v18
	v_fma_f32 v10, v18, v15, -v8
	v_fmac_f32_e32 v10, v18, v16
	v_sub_f32_e32 v9, v9, v5
	v_add_f32_e32 v15, v4, v9
	v_add_f32_e32 v4, v8, v10
	v_sub_f32_e32 v9, v5, v4
	v_pk_add_f32 v[12:13], v[4:5], v[8:9] neg_lo:[0,1] neg_hi:[0,1]
	v_mov_b32_e32 v11, v4
	v_pk_add_f32 v[4:5], v[12:13], v[10:11] neg_lo:[0,1] neg_hi:[0,1]
	s_nop 0
	v_add_f32_e32 v5, v15, v5
	v_add_f32_e32 v4, v4, v5
	v_add_f32_e32 v5, v19, v18
	v_add_f32_e32 v4, v9, v4
	v_sub_f32_e32 v8, v5, v19
	v_mul_f32_e32 v4, v17, v4
	v_sub_f32_e32 v8, v18, v8
	v_add_f32_e32 v8, v8, v4
	v_add_f32_e32 v10, v5, v8
	v_mul_f32_e32 v11, v10, v10
	v_fmamk_f32 v4, v11, 0x3e9b6dac, v152
	v_fmaak_f32 v35, v11, v4, 0x3f2aaada
	v_cvt_f32_i32_e32 v4, v14
	v_sub_f32_e32 v5, v10, v5
	v_sub_f32_e32 v5, v8, v5
	v_ldexp_f32 v12, v5, 1
	v_mul_f32_e32 v5, v10, v11
	v_ldexp_f32 v9, v10, 1
	v_pk_mul_f32 v[10:11], v[4:5], v[34:35]
	s_nop 0
	v_fma_f32 v8, v4, s5, -v10
	v_fmac_f32_e32 v8, 0xb102e308, v4
	v_pk_add_f32 v[4:5], v[10:11], v[8:9]
	s_nop 0
	v_sub_f32_e32 v9, v5, v9
	v_sub_f32_e32 v9, v11, v9
	v_add_f32_e32 v13, v12, v9
	v_mov_b32_e32 v12, v10
	v_pk_add_f32 v[10:11], v[4:5], v[10:11] neg_lo:[0,1] neg_hi:[0,1]
	v_pk_add_f32 v[14:15], v[4:5], v[12:13]
	v_mov_b32_e32 v9, v4
	v_mov_b32_e32 v11, v15
	v_pk_add_f32 v[16:17], v[8:9], v[10:11] neg_lo:[0,1] neg_hi:[0,1]
	v_pk_add_f32 v[8:9], v[8:9], v[10:11]
	v_mov_b32_e32 v12, v13
	v_pk_add_f32 v[10:11], v[8:9], v[4:5] op_sel:[1,0] op_sel_hi:[0,1] neg_lo:[0,1] neg_hi:[0,1]
	v_pk_add_f32 v[18:19], v[14:15], v[10:11] op_sel_hi:[1,0] neg_lo:[0,1] neg_hi:[0,1]
	v_mov_b32_e32 v14, v15
	v_mov_b32_e32 v15, v9
	v_pk_mov_b32 v[10:11], v[4:5], v[10:11] op_sel:[1,0]
	v_mov_b32_e32 v13, v4
	v_pk_add_f32 v[10:11], v[14:15], v[10:11] neg_lo:[0,1] neg_hi:[0,1]
	v_mov_b32_e32 v18, v16
	v_pk_add_f32 v[4:5], v[12:13], v[10:11] neg_lo:[0,1] neg_hi:[0,1]
	v_mov_b32_e32 v17, v9
	v_pk_add_f32 v[10:11], v[18:19], v[4:5]
	s_nop 0
	v_pk_add_f32 v[12:13], v[10:11], v[10:11] op_sel:[0,1] op_sel_hi:[1,0]
	s_nop 0
	v_pk_add_f32 v[8:9], v[8:9], v[12:13] op_sel:[1,0] op_sel_hi:[0,1]
	v_mov_b32_e32 v11, v8
	v_pk_add_f32 v[14:15], v[10:11], v[16:17] neg_lo:[0,1] neg_hi:[0,1]
	v_mov_b32_e32 v5, v12
	v_sub_f32_e32 v9, v10, v14
	v_pk_add_f32 v[4:5], v[4:5], v[14:15] neg_lo:[0,1] neg_hi:[0,1]
	v_sub_f32_e32 v9, v16, v9
	v_add_f32_e32 v4, v4, v9
	v_add_f32_e32 v4, v4, v5
	v_add_f32_e32 v4, v8, v4
	v_cndmask_b32_e32 v4, v153, v4, vcc
	v_cmp_ngt_f32_e32 vcc, -1.0, v1
	v_max_f32_e32 v14, v6, v6
	v_lshl_add_u64 v[10:11], s[34:35], 0, v[42:43]
	v_cndmask_b32_e32 v4, v154, v4, vcc
	v_cmp_neq_f32_e32 vcc, -1.0, v1
	v_lshl_add_u64 v[10:11], v[10:11], 0, v[2:3]
	s_nop 0
	v_cndmask_b32_e32 v4, v155, v4, vcc
	v_cmp_lt_f32_e64 vcc, |v1|, s50
	s_nop 1
	v_cndmask_b32_e32 v1, v4, v1, vcc
	v_sub_f32_e32 v1, v20, v1
	v_pk_add_f32 v[44:45], v[0:1], v[32:33]
	s_nop 0
	v_sub_f32_e32 v26, v44, v45
	v_max_f32_e32 v4, 0xff800000, v26
	v_max_f32_e32 v44, v14, v4
	v_sub_f32_e32 v1, v6, v44
	v_mul_f32_e32 v1, 0x3fb8aa3b, v1
	v_exp_f32_e32 v8, v1
	v_mov_b32_e32 v12, v186
	v_mov_b32_e32 v1, v187
	s_waitcnt vmcnt(0) lgkmcnt(0)
	v_add_f32_e32 v1, v7, v1
	v_min_f32_e32 v5, 0, v1
	v_mul_f32_e64 v1, |v1|, s1
	v_exp_f32_e32 v1, v1
	s_nop 0
	v_add_f32_e32 v9, 1.0, v1
	v_add_f32_e32 v10, -1.0, v9
	v_sub_f32_e32 v11, v10, v9
	v_add_f32_e32 v11, 1.0, v11
	v_sub_f32_e32 v10, v1, v10
	v_add_f32_e32 v13, v10, v11
	v_frexp_mant_f32_e32 v10, v9
	v_cmp_gt_f32_e32 vcc, s4, v10
	v_cvt_f64_f32_e32 v[10:11], v9
	v_frexp_exp_i32_f64_e32 v10, v[10:11]
	v_subbrev_co_u32_e32 v15, vcc, 0, v10, vcc
	v_sub_u32_e32 v10, 0, v15
	v_ldexp_f32 v9, v9, v10
	v_ldexp_f32 v10, v13, v10
	v_add_f32_e32 v13, -1.0, v9
	v_add_f32_e32 v11, 1.0, v13
	v_sub_f32_e32 v11, v9, v11
	v_add_f32_e32 v16, v10, v11
	v_add_f32_e32 v11, 1.0, v9
	v_add_f32_e32 v17, -1.0, v11
	v_sub_f32_e32 v9, v9, v17
	v_add_f32_e32 v9, v10, v9
	v_add_f32_e32 v22, v11, v9
	v_rcp_f32_e32 v23, v22
	v_sub_f32_e32 v10, v22, v11
	v_add_f32_e32 v11, v13, v16
	v_sub_f32_e32 v9, v9, v10
	v_sub_f32_e32 v10, v11, v13
	v_mul_f32_e32 v24, v11, v23
	v_sub_f32_e32 v13, v16, v10
	v_mul_f32_e32 v16, v22, v24
	v_fma_f32 v18, v24, v22, -v16
	v_fmac_f32_e32 v18, v24, v9
	v_add_f32_e32 v10, v16, v18
	v_sub_f32_e32 v17, v11, v10
	v_pk_add_f32 v[20:21], v[10:11], v[16:17] neg_lo:[0,1] neg_hi:[0,1]
	v_mov_b32_e32 v19, v10
	v_pk_add_f32 v[10:11], v[20:21], v[18:19] neg_lo:[0,1] neg_hi:[0,1]
	v_cmp_neq_f32_e32 vcc, s45, v1
	v_add_f32_e32 v11, v13, v11
	v_add_f32_e32 v10, v10, v11
	v_add_f32_e32 v11, v17, v10
	v_mul_f32_e32 v13, v23, v11
	v_mul_f32_e32 v16, v22, v13
	v_fma_f32 v18, v13, v22, -v16
	v_fmac_f32_e32 v18, v13, v9
	v_sub_f32_e32 v9, v17, v11
	v_add_f32_e32 v9, v10, v9
	v_add_f32_e32 v10, v16, v18
	v_sub_f32_e32 v17, v11, v10
	v_pk_add_f32 v[20:21], v[10:11], v[16:17] neg_lo:[0,1] neg_hi:[0,1]
	v_mov_b32_e32 v19, v10
	v_pk_add_f32 v[10:11], v[20:21], v[18:19] neg_lo:[0,1] neg_hi:[0,1]
	s_nop 0
	v_add_f32_e32 v9, v9, v11
	v_add_f32_e32 v9, v10, v9
	v_add_f32_e32 v11, v24, v13
	v_add_f32_e32 v9, v17, v9
	v_sub_f32_e32 v10, v11, v24
	v_mul_f32_e32 v9, v23, v9
	v_sub_f32_e32 v10, v13, v10
	v_add_f32_e32 v9, v10, v9
	v_add_f32_e32 v13, v11, v9
	v_mul_f32_e32 v16, v13, v13
	v_fmamk_f32 v10, v16, 0x3e9b6dac, v152
	v_fmaak_f32 v35, v16, v10, 0x3f2aaada
	v_cvt_f32_i32_e32 v10, v15
	v_sub_f32_e32 v11, v13, v11
	v_sub_f32_e32 v9, v9, v11
	v_mul_f32_e32 v11, v13, v16
	v_pk_mul_f32 v[18:19], v[10:11], v[34:35]
	v_ldexp_f32 v17, v13, 1
	v_fma_f32 v16, v10, s5, -v18
	v_fmac_f32_e32 v16, 0xb102e308, v10
	v_pk_add_f32 v[10:11], v[18:19], v[16:17]
	v_ldexp_f32 v9, v9, 1
	v_sub_f32_e32 v13, v11, v17
	v_sub_f32_e32 v13, v19, v13
	v_add_f32_e32 v21, v9, v13
	v_mov_b32_e32 v20, v18
	v_pk_add_f32 v[18:19], v[10:11], v[18:19] neg_lo:[0,1] neg_hi:[0,1]
	v_pk_add_f32 v[22:23], v[10:11], v[20:21]
	v_mov_b32_e32 v17, v10
	v_mov_b32_e32 v19, v23
	v_pk_add_f32 v[24:25], v[16:17], v[18:19] neg_lo:[0,1] neg_hi:[0,1]
	v_pk_add_f32 v[16:17], v[16:17], v[18:19]
	v_mov_b32_e32 v20, v21
	v_pk_add_f32 v[18:19], v[16:17], v[10:11] op_sel:[1,0] op_sel_hi:[0,1] neg_lo:[0,1] neg_hi:[0,1]
	v_pk_add_f32 v[28:29], v[22:23], v[18:19] op_sel_hi:[1,0] neg_lo:[0,1] neg_hi:[0,1]
	v_mov_b32_e32 v22, v23
	v_mov_b32_e32 v23, v17
	v_pk_mov_b32 v[18:19], v[10:11], v[18:19] op_sel:[1,0]
	v_mov_b32_e32 v21, v10
	v_pk_add_f32 v[18:19], v[22:23], v[18:19] neg_lo:[0,1] neg_hi:[0,1]
	v_mov_b32_e32 v28, v24
	v_pk_add_f32 v[10:11], v[20:21], v[18:19] neg_lo:[0,1] neg_hi:[0,1]
	v_mov_b32_e32 v25, v17
	v_pk_add_f32 v[18:19], v[28:29], v[10:11]
	s_nop 0
	v_pk_add_f32 v[20:21], v[18:19], v[18:19] op_sel:[0,1] op_sel_hi:[1,0]
	s_nop 0
	v_pk_add_f32 v[16:17], v[16:17], v[20:21] op_sel:[1,0] op_sel_hi:[0,1]
	v_mov_b32_e32 v19, v16
	v_pk_add_f32 v[22:23], v[18:19], v[24:25] neg_lo:[0,1] neg_hi:[0,1]
	v_mov_b32_e32 v11, v20
	v_sub_f32_e32 v9, v18, v22
	v_pk_add_f32 v[10:11], v[10:11], v[22:23] neg_lo:[0,1] neg_hi:[0,1]
	v_sub_f32_e32 v9, v24, v9
	v_add_f32_e32 v9, v10, v9
	v_add_f32_e32 v9, v9, v11
	v_add_f32_e32 v9, v16, v9
	v_cndmask_b32_e32 v9, v153, v9, vcc
	v_cmp_ngt_f32_e32 vcc, -1.0, v1
	v_lshl_add_u64 v[10:11], s[34:35], 0, v[48:49]
	v_lshl_add_u64 v[10:11], v[10:11], 0, v[2:3]
	v_cndmask_b32_e32 v9, v154, v9, vcc
	v_cmp_neq_f32_e32 vcc, -1.0, v1
	s_nop 1
	v_cndmask_b32_e32 v9, v155, v9, vcc
	v_cmp_lt_f32_e64 vcc, |v1|, s50
	s_nop 1
	v_cndmask_b32_e32 v1, v9, v1, vcc
	v_sub_f32_e32 v13, v5, v1
	v_mov_b32_e32 v1, v45
	v_pk_add_f32 v[52:53], v[0:1], v[12:13]
	s_nop 0
	v_sub_f32_e32 v27, v52, v53
	v_max_f32_e32 v4, v4, v27
	v_max_f32_e32 v52, v14, v4
	v_sub_f32_e32 v1, v6, v52
	v_mul_f32_e32 v1, 0x3fb8aa3b, v1
	v_exp_f32_e32 v9, v1
	v_mov_b32_e32 v12, v188
	v_mov_b32_e32 v1, v189
	s_waitcnt vmcnt(0) lgkmcnt(0)
	v_add_f32_e32 v1, v7, v1
	v_min_f32_e32 v5, 0, v1
	v_mul_f32_e64 v1, |v1|, s1
	v_exp_f32_e32 v1, v1
	s_nop 0
	v_add_f32_e32 v13, 1.0, v1
	v_add_f32_e32 v10, -1.0, v13
	v_sub_f32_e32 v11, v10, v13
	v_add_f32_e32 v11, 1.0, v11
	v_sub_f32_e32 v10, v1, v10
	v_add_f32_e32 v15, v10, v11
	v_frexp_mant_f32_e32 v10, v13
	v_cmp_gt_f32_e32 vcc, s4, v10
	v_cvt_f64_f32_e32 v[10:11], v13
	v_frexp_exp_i32_f64_e32 v10, v[10:11]
	v_subbrev_co_u32_e32 v22, vcc, 0, v10, vcc
	v_sub_u32_e32 v10, 0, v22
	v_ldexp_f32 v11, v13, v10
	v_add_f32_e32 v13, -1.0, v11
	v_add_f32_e32 v16, 1.0, v11
	v_ldexp_f32 v10, v15, v10
	v_add_f32_e32 v15, 1.0, v13
	v_add_f32_e32 v17, -1.0, v16
	v_sub_f32_e32 v15, v11, v15
	v_sub_f32_e32 v11, v11, v17
	v_add_f32_e32 v15, v10, v15
	v_add_f32_e32 v10, v10, v11
	v_add_f32_e32 v23, v16, v10
	v_rcp_f32_e32 v25, v23
	v_sub_f32_e32 v11, v23, v16
	v_sub_f32_e32 v24, v10, v11
	v_add_f32_e32 v11, v13, v15
	v_sub_f32_e32 v10, v11, v13
	v_sub_f32_e32 v13, v15, v10
	v_mul_f32_e32 v15, v11, v25
	v_mul_f32_e32 v16, v23, v15
	v_fma_f32 v18, v15, v23, -v16
	v_fmac_f32_e32 v18, v15, v24
	v_add_f32_e32 v10, v16, v18
	v_sub_f32_e32 v17, v11, v10
	v_pk_add_f32 v[20:21], v[10:11], v[16:17] neg_lo:[0,1] neg_hi:[0,1]
	v_mov_b32_e32 v19, v10
	v_pk_add_f32 v[10:11], v[20:21], v[18:19] neg_lo:[0,1] neg_hi:[0,1]
	v_cmp_neq_f32_e32 vcc, s45, v1
	v_add_f32_e32 v11, v13, v11
	v_add_f32_e32 v10, v10, v11
	v_add_f32_e32 v11, v17, v10
	v_mul_f32_e32 v13, v25, v11
	v_mul_f32_e32 v16, v23, v13
	v_fma_f32 v18, v13, v23, -v16
	v_fmac_f32_e32 v18, v13, v24
	v_sub_f32_e32 v17, v17, v11
	v_add_f32_e32 v23, v10, v17
	v_add_f32_e32 v10, v16, v18
	v_sub_f32_e32 v17, v11, v10
	v_pk_add_f32 v[20:21], v[10:11], v[16:17] neg_lo:[0,1] neg_hi:[0,1]
	v_mov_b32_e32 v19, v10
	v_pk_add_f32 v[10:11], v[20:21], v[18:19] neg_lo:[0,1] neg_hi:[0,1]
	s_nop 0
	v_add_f32_e32 v11, v23, v11
	v_add_f32_e32 v10, v10, v11
	v_add_f32_e32 v11, v15, v13
	v_add_f32_e32 v10, v17, v10
	v_sub_f32_e32 v15, v11, v15
	v_mul_f32_e32 v10, v25, v10
	v_sub_f32_e32 v13, v13, v15
	v_add_f32_e32 v13, v13, v10
	v_add_f32_e32 v15, v11, v13
	v_mul_f32_e32 v16, v15, v15
	v_fmamk_f32 v10, v16, 0x3e9b6dac, v152
	v_fmaak_f32 v35, v16, v10, 0x3f2aaada
	v_cvt_f32_i32_e32 v10, v22
	v_sub_f32_e32 v11, v15, v11
	v_sub_f32_e32 v11, v13, v11
	v_ldexp_f32 v13, v11, 1
	v_mul_f32_e32 v11, v15, v16
	v_pk_mul_f32 v[18:19], v[10:11], v[34:35]
	v_ldexp_f32 v17, v15, 1
	v_fma_f32 v16, v10, s5, -v18
	v_fmac_f32_e32 v16, 0xb102e308, v10
	v_pk_add_f32 v[10:11], v[18:19], v[16:17]
	v_mov_b32_e32 v20, v18
	v_sub_f32_e32 v15, v11, v17
	v_sub_f32_e32 v15, v19, v15
	v_add_f32_e32 v21, v13, v15
	v_pk_add_f32 v[18:19], v[10:11], v[18:19] neg_lo:[0,1] neg_hi:[0,1]
	v_pk_add_f32 v[22:23], v[10:11], v[20:21]
	v_mov_b32_e32 v17, v10
	v_mov_b32_e32 v19, v23
	v_pk_add_f32 v[24:25], v[16:17], v[18:19] neg_lo:[0,1] neg_hi:[0,1]
	v_pk_add_f32 v[16:17], v[16:17], v[18:19]
	v_mov_b32_e32 v20, v21
	v_pk_add_f32 v[18:19], v[16:17], v[10:11] op_sel:[1,0] op_sel_hi:[0,1] neg_lo:[0,1] neg_hi:[0,1]
	v_pk_add_f32 v[28:29], v[22:23], v[18:19] op_sel_hi:[1,0] neg_lo:[0,1] neg_hi:[0,1]
	v_mov_b32_e32 v22, v23
	v_mov_b32_e32 v23, v17
	v_pk_mov_b32 v[18:19], v[10:11], v[18:19] op_sel:[1,0]
	v_mov_b32_e32 v21, v10
	v_pk_add_f32 v[18:19], v[22:23], v[18:19] neg_lo:[0,1] neg_hi:[0,1]
	v_mov_b32_e32 v28, v24
	v_pk_add_f32 v[10:11], v[20:21], v[18:19] neg_lo:[0,1] neg_hi:[0,1]
	v_mov_b32_e32 v25, v17
	v_pk_add_f32 v[18:19], v[28:29], v[10:11]
	s_nop 0
	v_pk_add_f32 v[20:21], v[18:19], v[18:19] op_sel:[0,1] op_sel_hi:[1,0]
	s_nop 0
	v_pk_add_f32 v[16:17], v[16:17], v[20:21] op_sel:[1,0] op_sel_hi:[0,1]
	v_mov_b32_e32 v19, v16
	v_pk_add_f32 v[22:23], v[18:19], v[24:25] neg_lo:[0,1] neg_hi:[0,1]
	v_mov_b32_e32 v11, v20
	v_sub_f32_e32 v13, v18, v22
	v_pk_add_f32 v[10:11], v[10:11], v[22:23] neg_lo:[0,1] neg_hi:[0,1]
	v_sub_f32_e32 v13, v24, v13
	v_add_f32_e32 v10, v10, v13
	v_add_f32_e32 v10, v10, v11
	v_add_f32_e32 v10, v16, v10
	v_cndmask_b32_e32 v10, v153, v10, vcc
	v_cmp_ngt_f32_e32 vcc, -1.0, v1
	s_nop 1
	v_cndmask_b32_e32 v10, v154, v10, vcc
	v_cmp_neq_f32_e32 vcc, -1.0, v1
	s_nop 1
	v_cndmask_b32_e32 v10, v155, v10, vcc
	v_cmp_lt_f32_e64 vcc, |v1|, s50
	s_nop 1
	v_cndmask_b32_e32 v1, v10, v1, vcc
	v_sub_f32_e32 v13, v5, v1
	v_mov_b32_e32 v1, v53
	v_pk_add_f32 v[58:59], v[0:1], v[12:13]
	s_nop 0
	v_sub_f32_e32 v28, v58, v59
	v_max_f32_e32 v11, v4, v28
	v_max_f32_e32 v58, v14, v11
	v_sub_f32_e32 v1, v6, v58
	v_lshl_add_u64 v[4:5], s[34:35], 0, v[54:55]
	v_mul_f32_e32 v1, 0x3fb8aa3b, v1
	v_lshl_add_u64 v[12:13], v[4:5], 0, v[2:3]
	v_exp_f32_e32 v10, v1
	v_mov_b32_e32 v4, v190
	v_mov_b32_e32 v1, v191
	s_waitcnt vmcnt(0) lgkmcnt(0)
	v_add_f32_e32 v1, v7, v1
	v_min_f32_e32 v5, 0, v1
	v_mul_f32_e64 v1, |v1|, s1
	v_exp_f32_e32 v1, v1
	s_nop 0
	v_add_f32_e32 v15, 1.0, v1
	v_add_f32_e32 v12, -1.0, v15
	v_sub_f32_e32 v13, v12, v15
	v_add_f32_e32 v13, 1.0, v13
	v_sub_f32_e32 v12, v1, v12
	v_add_f32_e32 v16, v12, v13
	v_frexp_mant_f32_e32 v12, v15
	v_cmp_gt_f32_e32 vcc, s4, v12
	v_cvt_f64_f32_e32 v[12:13], v15
	v_frexp_exp_i32_f64_e32 v12, v[12:13]
	v_subbrev_co_u32_e32 v22, vcc, 0, v12, vcc
	v_sub_u32_e32 v12, 0, v22
	v_ldexp_f32 v13, v15, v12
	v_add_f32_e32 v15, -1.0, v13
	v_add_f32_e32 v17, 1.0, v13
	v_ldexp_f32 v12, v16, v12
	v_add_f32_e32 v16, 1.0, v15
	v_add_f32_e32 v18, -1.0, v17
	v_sub_f32_e32 v16, v13, v16
	v_sub_f32_e32 v13, v13, v18
	v_add_f32_e32 v16, v12, v16
	v_add_f32_e32 v12, v12, v13
	v_add_f32_e32 v23, v17, v12
	v_rcp_f32_e32 v25, v23
	v_sub_f32_e32 v13, v23, v17
	v_sub_f32_e32 v24, v12, v13
	v_add_f32_e32 v13, v15, v16
	v_sub_f32_e32 v12, v13, v15
	v_mul_f32_e32 v29, v13, v25
	v_sub_f32_e32 v15, v16, v12
	v_mul_f32_e32 v16, v23, v29
	v_fma_f32 v18, v29, v23, -v16
	v_fmac_f32_e32 v18, v29, v24
	v_add_f32_e32 v12, v16, v18
	v_sub_f32_e32 v17, v13, v12
	v_pk_add_f32 v[20:21], v[12:13], v[16:17] neg_lo:[0,1] neg_hi:[0,1]
	v_mov_b32_e32 v19, v12
	v_pk_add_f32 v[12:13], v[20:21], v[18:19] neg_lo:[0,1] neg_hi:[0,1]
	v_cmp_neq_f32_e32 vcc, s45, v1
	v_add_f32_e32 v13, v15, v13
	v_add_f32_e32 v12, v12, v13
	v_add_f32_e32 v13, v17, v12
	v_mul_f32_e32 v15, v25, v13
	v_mul_f32_e32 v16, v23, v15
	v_fma_f32 v18, v15, v23, -v16
	v_fmac_f32_e32 v18, v15, v24
	v_sub_f32_e32 v17, v17, v13
	v_add_f32_e32 v23, v12, v17
	v_add_f32_e32 v12, v16, v18
	v_sub_f32_e32 v17, v13, v12
	v_pk_add_f32 v[20:21], v[12:13], v[16:17] neg_lo:[0,1] neg_hi:[0,1]
	v_mov_b32_e32 v19, v12
	v_pk_add_f32 v[12:13], v[20:21], v[18:19] neg_lo:[0,1] neg_hi:[0,1]
	s_nop 0
	v_add_f32_e32 v13, v23, v13
	v_add_f32_e32 v12, v12, v13
	v_add_f32_e32 v13, v29, v15
	v_add_f32_e32 v12, v17, v12
	v_sub_f32_e32 v16, v13, v29
	v_mul_f32_e32 v12, v25, v12
	v_sub_f32_e32 v15, v15, v16
	v_add_f32_e32 v15, v15, v12
	v_add_f32_e32 v16, v13, v15
	v_mul_f32_e32 v18, v16, v16
	v_fmamk_f32 v12, v18, 0x3e9b6dac, v152
	v_fmaak_f32 v35, v18, v12, 0x3f2aaada
	v_cvt_f32_i32_e32 v12, v22
	v_sub_f32_e32 v13, v16, v13
	v_sub_f32_e32 v13, v15, v13
	v_ldexp_f32 v15, v13, 1
	v_mul_f32_e32 v13, v16, v18
	v_pk_mul_f32 v[18:19], v[12:13], v[34:35]
	v_ldexp_f32 v17, v16, 1
	v_fma_f32 v16, v12, s5, -v18
	v_fmac_f32_e32 v16, 0xb102e308, v12
	v_pk_add_f32 v[12:13], v[18:19], v[16:17]
	v_mov_b32_e32 v20, v18
	v_sub_f32_e32 v17, v13, v17
	v_sub_f32_e32 v17, v19, v17
	v_add_f32_e32 v21, v15, v17
	v_pk_add_f32 v[18:19], v[12:13], v[18:19] neg_lo:[0,1] neg_hi:[0,1]
	v_pk_add_f32 v[22:23], v[12:13], v[20:21]
	v_mov_b32_e32 v17, v12
	v_mov_b32_e32 v19, v23
	v_pk_add_f32 v[24:25], v[16:17], v[18:19] neg_lo:[0,1] neg_hi:[0,1]
	v_pk_add_f32 v[16:17], v[16:17], v[18:19]
	v_mov_b32_e32 v20, v21
	v_pk_add_f32 v[18:19], v[16:17], v[12:13] op_sel:[1,0] op_sel_hi:[0,1] neg_lo:[0,1] neg_hi:[0,1]
	v_pk_add_f32 v[30:31], v[22:23], v[18:19] op_sel_hi:[1,0] neg_lo:[0,1] neg_hi:[0,1]
	v_mov_b32_e32 v22, v23
	v_mov_b32_e32 v23, v17
	v_pk_mov_b32 v[18:19], v[12:13], v[18:19] op_sel:[1,0]
	v_mov_b32_e32 v21, v12
	v_pk_add_f32 v[18:19], v[22:23], v[18:19] neg_lo:[0,1] neg_hi:[0,1]
	v_mov_b32_e32 v30, v24
	v_pk_add_f32 v[12:13], v[20:21], v[18:19] neg_lo:[0,1] neg_hi:[0,1]
	v_mov_b32_e32 v25, v17
	v_pk_add_f32 v[18:19], v[30:31], v[12:13]
	s_nop 0
	v_pk_add_f32 v[20:21], v[18:19], v[18:19] op_sel:[0,1] op_sel_hi:[1,0]
	s_nop 0
	v_pk_add_f32 v[16:17], v[16:17], v[20:21] op_sel:[1,0] op_sel_hi:[0,1]
	v_mov_b32_e32 v19, v16
	v_pk_add_f32 v[22:23], v[18:19], v[24:25] neg_lo:[0,1] neg_hi:[0,1]
	v_mov_b32_e32 v13, v20
	v_sub_f32_e32 v15, v18, v22
	v_pk_add_f32 v[12:13], v[12:13], v[22:23] neg_lo:[0,1] neg_hi:[0,1]
	v_sub_f32_e32 v15, v24, v15
	v_add_f32_e32 v12, v12, v15
	v_add_f32_e32 v12, v12, v13
	v_add_f32_e32 v12, v16, v12
	v_cndmask_b32_e32 v12, v153, v12, vcc
	v_cmp_ngt_f32_e32 vcc, -1.0, v1
	s_nop 1
	v_cndmask_b32_e32 v12, v154, v12, vcc
	v_cmp_neq_f32_e32 vcc, -1.0, v1
	s_nop 1
	v_cndmask_b32_e32 v12, v155, v12, vcc
	v_cmp_lt_f32_e64 vcc, |v1|, s50
	s_nop 1
	v_cndmask_b32_e32 v1, v12, v1, vcc
	v_sub_f32_e32 v5, v5, v1
	v_mov_b32_e32 v1, v59
	v_pk_add_f32 v[66:67], v[0:1], v[4:5]
	v_lshl_add_u64 v[4:5], s[34:35], 0, v[60:61]
	v_sub_f32_e32 v29, v66, v67
	v_max_f32_e32 v15, v11, v29
	v_max_f32_e32 v66, v14, v15
	v_sub_f32_e32 v1, v6, v66
	v_mul_f32_e32 v1, 0x3fb8aa3b, v1
	v_lshl_add_u64 v[4:5], v[4:5], 0, v[2:3]
	v_exp_f32_e32 v11, v1
	v_mov_b32_e32 v12, v192
	v_mov_b32_e32 v1, v193
	s_waitcnt vmcnt(0) lgkmcnt(0)
	v_add_f32_e32 v1, v7, v1
	v_min_f32_e32 v13, 0, v1
	v_mul_f32_e64 v1, |v1|, s1
	v_exp_f32_e32 v1, v1
	s_nop 0
	v_add_f32_e32 v16, 1.0, v1
	v_add_f32_e32 v4, -1.0, v16
	v_sub_f32_e32 v5, v4, v16
	v_add_f32_e32 v5, 1.0, v5
	v_sub_f32_e32 v4, v1, v4
	v_add_f32_e32 v17, v4, v5
	v_frexp_mant_f32_e32 v4, v16
	v_cmp_gt_f32_e32 vcc, s4, v4
	v_cvt_f64_f32_e32 v[4:5], v16
	v_frexp_exp_i32_f64_e32 v4, v[4:5]
	v_subbrev_co_u32_e32 v22, vcc, 0, v4, vcc
	v_sub_u32_e32 v4, 0, v22
	v_ldexp_f32 v5, v16, v4
	v_add_f32_e32 v16, -1.0, v5
	v_add_f32_e32 v18, 1.0, v5
	v_ldexp_f32 v4, v17, v4
	v_add_f32_e32 v17, 1.0, v16
	v_add_f32_e32 v19, -1.0, v18
	v_sub_f32_e32 v17, v5, v17
	v_sub_f32_e32 v5, v5, v19
	v_add_f32_e32 v17, v4, v17
	v_add_f32_e32 v4, v4, v5
	v_add_f32_e32 v23, v18, v4
	v_rcp_f32_e32 v25, v23
	v_sub_f32_e32 v5, v23, v18
	v_sub_f32_e32 v24, v4, v5
	v_add_f32_e32 v5, v16, v17
	v_mul_f32_e32 v31, v5, v25
	v_sub_f32_e32 v4, v5, v16
	v_mul_f32_e32 v16, v23, v31
	v_fma_f32 v18, v31, v23, -v16
	v_fmac_f32_e32 v18, v31, v24
	v_sub_f32_e32 v30, v17, v4
	v_add_f32_e32 v4, v16, v18
	v_sub_f32_e32 v17, v5, v4
	v_pk_add_f32 v[20:21], v[4:5], v[16:17] neg_lo:[0,1] neg_hi:[0,1]
	v_mov_b32_e32 v19, v4
	v_pk_add_f32 v[4:5], v[20:21], v[18:19] neg_lo:[0,1] neg_hi:[0,1]
	v_cmp_neq_f32_e32 vcc, s45, v1
	v_add_f32_e32 v5, v30, v5
	v_add_f32_e32 v4, v4, v5
	v_add_f32_e32 v5, v17, v4
	v_mul_f32_e32 v30, v25, v5
	v_mul_f32_e32 v16, v23, v30
	v_fma_f32 v18, v30, v23, -v16
	v_fmac_f32_e32 v18, v30, v24
	v_sub_f32_e32 v17, v17, v5
	v_add_f32_e32 v23, v4, v17
	v_add_f32_e32 v4, v16, v18
	v_sub_f32_e32 v17, v5, v4
	v_pk_add_f32 v[20:21], v[4:5], v[16:17] neg_lo:[0,1] neg_hi:[0,1]
	v_mov_b32_e32 v19, v4
	v_pk_add_f32 v[4:5], v[20:21], v[18:19] neg_lo:[0,1] neg_hi:[0,1]
	s_nop 0
	v_add_f32_e32 v5, v23, v5
	v_add_f32_e32 v4, v4, v5
	v_add_f32_e32 v5, v31, v30
	v_add_f32_e32 v4, v17, v4
	v_sub_f32_e32 v16, v5, v31
	v_mul_f32_e32 v4, v25, v4
	v_sub_f32_e32 v16, v30, v16
	v_add_f32_e32 v16, v16, v4
	v_add_f32_e32 v18, v5, v16
	v_mul_f32_e32 v19, v18, v18
	v_fmamk_f32 v4, v19, 0x3e9b6dac, v152
	v_fmaak_f32 v35, v19, v4, 0x3f2aaada
	v_cvt_f32_i32_e32 v4, v22
	v_sub_f32_e32 v5, v18, v5
	v_sub_f32_e32 v5, v16, v5
	v_ldexp_f32 v20, v5, 1
	v_mul_f32_e32 v5, v18, v19
	v_ldexp_f32 v17, v18, 1
	v_pk_mul_f32 v[18:19], v[4:5], v[34:35]
	s_nop 0
	v_fma_f32 v16, v4, s5, -v18
	v_fmac_f32_e32 v16, 0xb102e308, v4
	v_pk_add_f32 v[4:5], v[18:19], v[16:17]
	s_nop 0
	v_sub_f32_e32 v17, v5, v17
	v_sub_f32_e32 v17, v19, v17
	v_add_f32_e32 v21, v20, v17
	v_mov_b32_e32 v20, v18
	v_pk_add_f32 v[18:19], v[4:5], v[18:19] neg_lo:[0,1] neg_hi:[0,1]
	v_pk_add_f32 v[22:23], v[4:5], v[20:21]
	v_mov_b32_e32 v17, v4
	v_mov_b32_e32 v19, v23
	v_pk_add_f32 v[24:25], v[16:17], v[18:19] neg_lo:[0,1] neg_hi:[0,1]
	v_pk_add_f32 v[16:17], v[16:17], v[18:19]
	v_mov_b32_e32 v20, v21
	v_pk_add_f32 v[18:19], v[16:17], v[4:5] op_sel:[1,0] op_sel_hi:[0,1] neg_lo:[0,1] neg_hi:[0,1]
	v_pk_add_f32 v[30:31], v[22:23], v[18:19] op_sel_hi:[1,0] neg_lo:[0,1] neg_hi:[0,1]
	v_mov_b32_e32 v22, v23
	v_mov_b32_e32 v23, v17
	v_pk_mov_b32 v[18:19], v[4:5], v[18:19] op_sel:[1,0]
	v_mov_b32_e32 v21, v4
	v_pk_add_f32 v[18:19], v[22:23], v[18:19] neg_lo:[0,1] neg_hi:[0,1]
	v_mov_b32_e32 v30, v24
	v_pk_add_f32 v[4:5], v[20:21], v[18:19] neg_lo:[0,1] neg_hi:[0,1]
	v_mov_b32_e32 v25, v17
	v_pk_add_f32 v[18:19], v[30:31], v[4:5]
	s_nop 0
	v_pk_add_f32 v[20:21], v[18:19], v[18:19] op_sel:[0,1] op_sel_hi:[1,0]
	s_nop 0
	v_pk_add_f32 v[16:17], v[16:17], v[20:21] op_sel:[1,0] op_sel_hi:[0,1]
	v_mov_b32_e32 v19, v16
	v_pk_add_f32 v[22:23], v[18:19], v[24:25] neg_lo:[0,1] neg_hi:[0,1]
	v_mov_b32_e32 v5, v20
	v_sub_f32_e32 v17, v18, v22
	v_pk_add_f32 v[4:5], v[4:5], v[22:23] neg_lo:[0,1] neg_hi:[0,1]
	v_sub_f32_e32 v17, v24, v17
	v_add_f32_e32 v4, v4, v17
	v_add_f32_e32 v4, v4, v5
	v_add_f32_e32 v4, v16, v4
	v_cndmask_b32_e32 v4, v153, v4, vcc
	v_cmp_ngt_f32_e32 vcc, -1.0, v1
	v_lshl_add_u64 v[16:17], s[34:35], 0, v[64:65]
	v_lshl_add_u64 v[16:17], v[16:17], 0, v[2:3]
	v_cndmask_b32_e32 v4, v154, v4, vcc
	v_cmp_neq_f32_e32 vcc, -1.0, v1
	s_nop 1
	v_cndmask_b32_e32 v4, v155, v4, vcc
	v_cmp_lt_f32_e64 vcc, |v1|, s50
	s_nop 1
	v_cndmask_b32_e32 v1, v4, v1, vcc
	v_sub_f32_e32 v13, v13, v1
	v_mov_b32_e32 v1, v67
	v_pk_add_f32 v[68:69], v[0:1], v[12:13]
	s_nop 0
	v_sub_f32_e32 v30, v68, v69
	v_max_f32_e32 v4, v15, v30
	v_max_f32_e32 v68, v14, v4
	v_sub_f32_e32 v1, v6, v68
	v_mul_f32_e32 v1, 0x3fb8aa3b, v1
	v_exp_f32_e32 v12, v1
	v_mov_b32_e32 v18, v194
	v_mov_b32_e32 v1, v195
	s_waitcnt vmcnt(0) lgkmcnt(0)
	v_add_f32_e32 v1, v7, v1
	v_min_f32_e32 v5, 0, v1
	v_mul_f32_e64 v1, |v1|, s1
	v_exp_f32_e32 v1, v1
	s_nop 0
	v_add_f32_e32 v13, 1.0, v1
	v_add_f32_e32 v15, -1.0, v13
	v_sub_f32_e32 v16, v15, v13
	v_add_f32_e32 v16, 1.0, v16
	v_sub_f32_e32 v15, v1, v15
	v_add_f32_e32 v15, v15, v16
	v_frexp_mant_f32_e32 v16, v13
	v_cmp_gt_f32_e32 vcc, s4, v16
	v_cvt_f64_f32_e32 v[16:17], v13
	v_frexp_exp_i32_f64_e32 v16, v[16:17]
	v_subbrev_co_u32_e32 v19, vcc, 0, v16, vcc
	v_sub_u32_e32 v16, 0, v19
	v_ldexp_f32 v13, v13, v16
	v_ldexp_f32 v15, v15, v16
	v_add_f32_e32 v16, -1.0, v13
	v_add_f32_e32 v17, 1.0, v16
	v_sub_f32_e32 v17, v13, v17
	v_add_f32_e32 v20, v15, v17
	v_add_f32_e32 v17, 1.0, v13
	v_add_f32_e32 v21, -1.0, v17
	v_sub_f32_e32 v13, v13, v21
	v_add_f32_e32 v13, v15, v13
	v_add_f32_e32 v15, v17, v13
	v_rcp_f32_e32 v31, v15
	v_sub_f32_e32 v17, v15, v17
	v_sub_f32_e32 v13, v13, v17
	v_add_f32_e32 v17, v16, v20
	v_sub_f32_e32 v16, v17, v16
	v_mul_f32_e32 v35, v17, v31
	v_sub_f32_e32 v32, v20, v16
	v_mul_f32_e32 v20, v15, v35
	v_fma_f32 v22, v35, v15, -v20
	v_fmac_f32_e32 v22, v35, v13
	v_add_f32_e32 v16, v20, v22
	v_sub_f32_e32 v21, v17, v16
	v_pk_add_f32 v[24:25], v[16:17], v[20:21] neg_lo:[0,1] neg_hi:[0,1]
	v_mov_b32_e32 v23, v16
	v_pk_add_f32 v[16:17], v[24:25], v[22:23] neg_lo:[0,1] neg_hi:[0,1]
	v_cmp_neq_f32_e32 vcc, s45, v1
	v_add_f32_e32 v17, v32, v17
	v_add_f32_e32 v16, v16, v17
	v_add_f32_e32 v17, v21, v16
	v_mul_f32_e32 v32, v31, v17
	v_mul_f32_e32 v20, v15, v32
	v_fma_f32 v22, v32, v15, -v20
	v_fmac_f32_e32 v22, v32, v13
	v_sub_f32_e32 v13, v21, v17
	v_add_f32_e32 v13, v16, v13
	v_add_f32_e32 v16, v20, v22
	v_sub_f32_e32 v21, v17, v16
	v_pk_add_f32 v[24:25], v[16:17], v[20:21] neg_lo:[0,1] neg_hi:[0,1]
	v_mov_b32_e32 v23, v16
	v_pk_add_f32 v[16:17], v[24:25], v[22:23] neg_lo:[0,1] neg_hi:[0,1]
	v_add_f32_e32 v15, v35, v32
	v_add_f32_e32 v13, v13, v17
	v_add_f32_e32 v13, v16, v13
	v_add_f32_e32 v13, v21, v13
	v_sub_f32_e32 v16, v15, v35
	v_mul_f32_e32 v13, v31, v13
	v_sub_f32_e32 v16, v32, v16
	v_add_f32_e32 v13, v16, v13
	v_add_f32_e32 v17, v15, v13
	v_mul_f32_e32 v20, v17, v17
	v_fmamk_f32 v16, v20, 0x3e9b6dac, v152
	v_fmaak_f32 v35, v20, v16, 0x3f2aaada
	v_cvt_f32_i32_e32 v16, v19
	v_sub_f32_e32 v15, v17, v15
	v_ldexp_f32 v21, v17, 1
	v_mul_f32_e32 v17, v17, v20
	v_pk_mul_f32 v[22:23], v[16:17], v[34:35]
	v_sub_f32_e32 v13, v13, v15
	v_fma_f32 v20, v16, s5, -v22
	v_fmac_f32_e32 v20, 0xb102e308, v16
	v_pk_add_f32 v[16:17], v[22:23], v[20:21]
	v_ldexp_f32 v13, v13, 1
	v_sub_f32_e32 v15, v17, v21
	v_sub_f32_e32 v15, v23, v15
	v_add_f32_e32 v25, v13, v15
	v_mov_b32_e32 v24, v22
	v_pk_add_f32 v[22:23], v[16:17], v[22:23] neg_lo:[0,1] neg_hi:[0,1]
	v_pk_add_f32 v[72:73], v[16:17], v[24:25]
	v_mov_b32_e32 v21, v16
	v_mov_b32_e32 v23, v73
	v_pk_add_f32 v[74:75], v[20:21], v[22:23] neg_lo:[0,1] neg_hi:[0,1]
	v_pk_add_f32 v[20:21], v[20:21], v[22:23]
	v_mov_b32_e32 v24, v25
	v_pk_add_f32 v[22:23], v[20:21], v[16:17] op_sel:[1,0] op_sel_hi:[0,1] neg_lo:[0,1] neg_hi:[0,1]
	v_pk_add_f32 v[76:77], v[72:73], v[22:23] op_sel_hi:[1,0] neg_lo:[0,1] neg_hi:[0,1]
	v_mov_b32_e32 v72, v73
	v_mov_b32_e32 v73, v21
	v_pk_mov_b32 v[22:23], v[16:17], v[22:23] op_sel:[1,0]
	v_mov_b32_e32 v25, v16
	v_pk_add_f32 v[22:23], v[72:73], v[22:23] neg_lo:[0,1] neg_hi:[0,1]
	v_mov_b32_e32 v76, v74
	v_pk_add_f32 v[16:17], v[24:25], v[22:23] neg_lo:[0,1] neg_hi:[0,1]
	v_mov_b32_e32 v75, v21
	v_pk_add_f32 v[22:23], v[76:77], v[16:17]
	s_nop 0
	v_pk_add_f32 v[24:25], v[22:23], v[22:23] op_sel:[0,1] op_sel_hi:[1,0]
	s_nop 0
	v_pk_add_f32 v[20:21], v[20:21], v[24:25] op_sel:[1,0] op_sel_hi:[0,1]
	v_mov_b32_e32 v23, v20
	v_pk_add_f32 v[72:73], v[22:23], v[74:75] neg_lo:[0,1] neg_hi:[0,1]
	v_mov_b32_e32 v17, v24
	v_sub_f32_e32 v13, v22, v72
	v_pk_add_f32 v[16:17], v[16:17], v[72:73] neg_lo:[0,1] neg_hi:[0,1]
	v_sub_f32_e32 v13, v74, v13
	v_add_f32_e32 v13, v16, v13
	v_add_f32_e32 v13, v13, v17
	v_add_f32_e32 v13, v20, v13
	v_cndmask_b32_e32 v13, v153, v13, vcc
	v_cmp_ngt_f32_e32 vcc, -1.0, v1
	v_add_u32_e32 v74, 6, v38
	v_ashrrev_i32_e32 v75, 31, v74
	v_cndmask_b32_e32 v13, v154, v13, vcc
	v_cmp_neq_f32_e32 vcc, -1.0, v1
	v_lshlrev_b64 v[72:73], 5, v[74:75]
	v_lshl_add_u64 v[16:17], s[34:35], 0, v[72:73]
	v_cndmask_b32_e32 v13, v155, v13, vcc
	v_cmp_lt_f32_e64 vcc, |v1|, s50
	v_lshl_add_u64 v[16:17], v[16:17], 0, v[2:3]
	s_nop 0
	v_cndmask_b32_e32 v1, v13, v1, vcc
	v_sub_f32_e32 v19, v5, v1
	v_mov_b32_e32 v1, v69
	v_pk_add_f32 v[76:77], v[0:1], v[18:19]
	s_nop 0
	v_sub_f32_e32 v31, v76, v77
	v_max_f32_e32 v4, v4, v31
	v_max_f32_e32 v76, v14, v4
	v_sub_f32_e32 v1, v6, v76
	v_mul_f32_e32 v1, 0x3fb8aa3b, v1
	v_exp_f32_e32 v13, v1
	v_mov_b32_e32 v18, v196
	v_mov_b32_e32 v1, v197
	s_waitcnt vmcnt(0) lgkmcnt(0)
	v_add_f32_e32 v1, v7, v1
	v_min_f32_e32 v5, 0, v1
	v_mul_f32_e64 v1, |v1|, s1
	v_exp_f32_e32 v1, v1
	s_nop 0
	v_add_f32_e32 v15, 1.0, v1
	v_add_f32_e32 v16, -1.0, v15
	v_sub_f32_e32 v17, v16, v15
	v_add_f32_e32 v17, 1.0, v17
	v_sub_f32_e32 v16, v1, v16
	v_add_f32_e32 v19, v16, v17
	v_frexp_mant_f32_e32 v16, v15
	v_cmp_gt_f32_e32 vcc, s4, v16
	v_cvt_f64_f32_e32 v[16:17], v15
	v_frexp_exp_i32_f64_e32 v16, v[16:17]
	v_subbrev_co_u32_e32 v32, vcc, 0, v16, vcc
	v_sub_u32_e32 v16, 0, v32
	v_ldexp_f32 v15, v15, v16
	v_ldexp_f32 v16, v19, v16
	v_add_f32_e32 v19, -1.0, v15
	v_add_f32_e32 v17, 1.0, v19
	v_sub_f32_e32 v17, v15, v17
	v_add_f32_e32 v20, v16, v17
	v_add_f32_e32 v17, 1.0, v15
	v_add_f32_e32 v21, -1.0, v17
	v_sub_f32_e32 v15, v15, v21
	v_add_f32_e32 v15, v16, v15
	v_add_f32_e32 v35, v17, v15
	v_rcp_f32_e32 v37, v35
	v_sub_f32_e32 v16, v35, v17
	v_add_f32_e32 v17, v19, v20
	v_sub_f32_e32 v15, v15, v16
	v_sub_f32_e32 v16, v17, v19
	v_mul_f32_e32 v78, v17, v37
	v_sub_f32_e32 v19, v20, v16
	v_mul_f32_e32 v20, v35, v78
	v_fma_f32 v22, v78, v35, -v20
	v_fmac_f32_e32 v22, v78, v15
	v_add_f32_e32 v16, v20, v22
	v_sub_f32_e32 v21, v17, v16
	v_pk_add_f32 v[24:25], v[16:17], v[20:21] neg_lo:[0,1] neg_hi:[0,1]
	v_mov_b32_e32 v23, v16
	v_pk_add_f32 v[16:17], v[24:25], v[22:23] neg_lo:[0,1] neg_hi:[0,1]
	v_cmp_neq_f32_e32 vcc, s45, v1
	v_add_f32_e32 v17, v19, v17
	v_add_f32_e32 v16, v16, v17
	v_add_f32_e32 v17, v21, v16
	v_mul_f32_e32 v19, v37, v17
	v_mul_f32_e32 v20, v35, v19
	v_fma_f32 v22, v19, v35, -v20
	v_fmac_f32_e32 v22, v19, v15
	v_sub_f32_e32 v15, v21, v17
	v_add_f32_e32 v15, v16, v15
	v_add_f32_e32 v16, v20, v22
	v_sub_f32_e32 v21, v17, v16
	v_pk_add_f32 v[24:25], v[16:17], v[20:21] neg_lo:[0,1] neg_hi:[0,1]
	v_mov_b32_e32 v23, v16
	v_pk_add_f32 v[16:17], v[24:25], v[22:23] neg_lo:[0,1] neg_hi:[0,1]
	s_nop 0
	v_add_f32_e32 v15, v15, v17
	v_add_f32_e32 v15, v16, v15
	v_add_f32_e32 v17, v78, v19
	v_add_f32_e32 v15, v21, v15
	v_sub_f32_e32 v16, v17, v78
	v_mul_f32_e32 v15, v37, v15
	v_sub_f32_e32 v16, v19, v16
	v_add_f32_e32 v15, v16, v15
	v_add_f32_e32 v19, v17, v15
	v_mul_f32_e32 v20, v19, v19
	v_fmamk_f32 v16, v20, 0x3e9b6dac, v152
	v_fmaak_f32 v35, v20, v16, 0x3f2aaada
	v_cvt_f32_i32_e32 v16, v32
	v_sub_f32_e32 v17, v19, v17
	v_sub_f32_e32 v15, v15, v17
	v_mul_f32_e32 v17, v19, v20
	v_pk_mul_f32 v[22:23], v[16:17], v[34:35]
	v_ldexp_f32 v21, v19, 1
	v_fma_f32 v20, v16, s5, -v22
	v_fmac_f32_e32 v20, 0xb102e308, v16
	v_pk_add_f32 v[16:17], v[22:23], v[20:21]
	v_ldexp_f32 v15, v15, 1
	v_sub_f32_e32 v19, v17, v21
	v_sub_f32_e32 v19, v23, v19
	v_add_f32_e32 v25, v15, v19
	v_mov_b32_e32 v24, v22
	v_pk_add_f32 v[22:23], v[16:17], v[22:23] neg_lo:[0,1] neg_hi:[0,1]
	v_pk_add_f32 v[78:79], v[16:17], v[24:25]
	v_mov_b32_e32 v21, v16
	v_mov_b32_e32 v23, v79
	v_pk_add_f32 v[80:81], v[20:21], v[22:23] neg_lo:[0,1] neg_hi:[0,1]
	v_pk_add_f32 v[20:21], v[20:21], v[22:23]
	v_mov_b32_e32 v24, v25
	v_pk_add_f32 v[22:23], v[20:21], v[16:17] op_sel:[1,0] op_sel_hi:[0,1] neg_lo:[0,1] neg_hi:[0,1]
	v_pk_add_f32 v[82:83], v[78:79], v[22:23] op_sel_hi:[1,0] neg_lo:[0,1] neg_hi:[0,1]
	v_mov_b32_e32 v78, v79
	v_mov_b32_e32 v79, v21
	v_pk_mov_b32 v[22:23], v[16:17], v[22:23] op_sel:[1,0]
	v_mov_b32_e32 v25, v16
	v_pk_add_f32 v[22:23], v[78:79], v[22:23] neg_lo:[0,1] neg_hi:[0,1]
	v_mov_b32_e32 v82, v80
	v_pk_add_f32 v[16:17], v[24:25], v[22:23] neg_lo:[0,1] neg_hi:[0,1]
	v_mov_b32_e32 v81, v21
	v_pk_add_f32 v[22:23], v[82:83], v[16:17]
	s_nop 0
	v_pk_add_f32 v[24:25], v[22:23], v[22:23] op_sel:[0,1] op_sel_hi:[1,0]
	s_nop 0
	v_pk_add_f32 v[20:21], v[20:21], v[24:25] op_sel:[1,0] op_sel_hi:[0,1]
	v_mov_b32_e32 v23, v20
	v_pk_add_f32 v[78:79], v[22:23], v[80:81] neg_lo:[0,1] neg_hi:[0,1]
	v_mov_b32_e32 v17, v24
	v_sub_f32_e32 v15, v22, v78
	v_pk_add_f32 v[16:17], v[16:17], v[78:79] neg_lo:[0,1] neg_hi:[0,1]
	v_sub_f32_e32 v15, v80, v15
	v_add_f32_e32 v15, v16, v15
	v_add_f32_e32 v15, v15, v17
	v_add_f32_e32 v15, v20, v15
	v_cndmask_b32_e32 v15, v153, v15, vcc
	v_cmp_ngt_f32_e32 vcc, -1.0, v1
	v_add_u32_e32 v80, 7, v38
	v_ashrrev_i32_e32 v81, 31, v80
	v_cndmask_b32_e32 v15, v154, v15, vcc
	v_cmp_neq_f32_e32 vcc, -1.0, v1
	v_lshlrev_b64 v[78:79], 5, v[80:81]
	v_lshl_add_u64 v[16:17], s[34:35], 0, v[78:79]
	v_cndmask_b32_e32 v15, v155, v15, vcc
	v_cmp_lt_f32_e64 vcc, |v1|, s50
	v_lshl_add_u64 v[16:17], v[16:17], 0, v[2:3]
	s_nop 0
	v_cndmask_b32_e32 v1, v15, v1, vcc
	v_sub_f32_e32 v19, v5, v1
	v_mov_b32_e32 v1, v77
	v_pk_add_f32 v[82:83], v[0:1], v[18:19]
	s_nop 0
	v_sub_f32_e32 v32, v82, v83
	v_max_f32_e32 v4, v4, v32
	v_max_f32_e32 v82, v14, v4
	v_sub_f32_e32 v1, v6, v82
	v_mul_f32_e32 v1, 0x3fb8aa3b, v1
	v_exp_f32_e32 v14, v1
	v_mov_b32_e32 v2, v198
	v_mov_b32_e32 v1, v199
	s_waitcnt vmcnt(0) lgkmcnt(0)
	v_add_f32_e32 v1, v7, v1
	v_min_f32_e32 v3, 0, v1
	v_mul_f32_e64 v1, |v1|, s1
	v_exp_f32_e32 v1, v1
	s_nop 0
	v_add_f32_e32 v5, 1.0, v1
	v_add_f32_e32 v7, -1.0, v5
	v_sub_f32_e32 v15, v7, v5
	v_add_f32_e32 v15, 1.0, v15
	v_sub_f32_e32 v7, v1, v7
	v_add_f32_e32 v7, v7, v15
	v_frexp_mant_f32_e32 v15, v5
	v_cvt_f64_f32_e32 v[16:17], v5
	v_cmp_gt_f32_e32 vcc, s4, v15
	v_frexp_exp_i32_f64_e32 v15, v[16:17]
	s_nop 0
	v_subbrev_co_u32_e32 v15, vcc, 0, v15, vcc
	v_sub_u32_e32 v16, 0, v15
	v_ldexp_f32 v5, v5, v16
	v_ldexp_f32 v7, v7, v16
	v_add_f32_e32 v16, -1.0, v5
	v_add_f32_e32 v17, 1.0, v16
	v_sub_f32_e32 v17, v5, v17
	v_add_f32_e32 v18, v7, v17
	v_add_f32_e32 v17, 1.0, v5
	v_add_f32_e32 v19, -1.0, v17
	v_sub_f32_e32 v5, v5, v19
	v_add_f32_e32 v5, v7, v5
	v_add_f32_e32 v7, v17, v5
	v_rcp_f32_e32 v24, v7
	v_sub_f32_e32 v17, v7, v17
	v_sub_f32_e32 v5, v5, v17
	v_add_f32_e32 v17, v16, v18
	v_sub_f32_e32 v16, v17, v16
	v_mul_f32_e32 v35, v17, v24
	v_sub_f32_e32 v25, v18, v16
	v_mul_f32_e32 v18, v7, v35
	v_fma_f32 v20, v35, v7, -v18
	v_fmac_f32_e32 v20, v35, v5
	v_add_f32_e32 v16, v18, v20
	v_sub_f32_e32 v19, v17, v16
	v_pk_add_f32 v[22:23], v[16:17], v[18:19] neg_lo:[0,1] neg_hi:[0,1]
	v_mov_b32_e32 v21, v16
	v_pk_add_f32 v[16:17], v[22:23], v[20:21] neg_lo:[0,1] neg_hi:[0,1]
	v_cmp_neq_f32_e32 vcc, s45, v1
	v_add_f32_e32 v17, v25, v17
	v_add_f32_e32 v16, v16, v17
	v_add_f32_e32 v17, v19, v16
	v_mul_f32_e32 v25, v24, v17
	v_mul_f32_e32 v18, v7, v25
	v_fma_f32 v20, v25, v7, -v18
	v_fmac_f32_e32 v20, v25, v5
	v_sub_f32_e32 v5, v19, v17
	v_add_f32_e32 v5, v16, v5
	v_add_f32_e32 v16, v18, v20
	v_sub_f32_e32 v19, v17, v16
	v_pk_add_f32 v[22:23], v[16:17], v[18:19] neg_lo:[0,1] neg_hi:[0,1]
	v_mov_b32_e32 v21, v16
	v_pk_add_f32 v[16:17], v[22:23], v[20:21] neg_lo:[0,1] neg_hi:[0,1]
	v_add_f32_e32 v7, v35, v25
	v_add_f32_e32 v5, v5, v17
	v_add_f32_e32 v5, v16, v5
	v_add_f32_e32 v5, v19, v5
	v_sub_f32_e32 v16, v7, v35
	v_mul_f32_e32 v5, v24, v5
	v_sub_f32_e32 v16, v25, v16
	v_add_f32_e32 v5, v16, v5
	v_add_f32_e32 v17, v7, v5
	v_mul_f32_e32 v18, v17, v17
	v_fmamk_f32 v16, v18, 0x3e9b6dac, v152
	v_fmaak_f32 v35, v18, v16, 0x3f2aaada
	v_cvt_f32_i32_e32 v16, v15
	v_sub_f32_e32 v7, v17, v7
	v_ldexp_f32 v19, v17, 1
	v_mul_f32_e32 v17, v17, v18
	v_pk_mul_f32 v[20:21], v[16:17], v[34:35]
	v_sub_f32_e32 v5, v5, v7
	v_fma_f32 v18, v16, s5, -v20
	v_fmac_f32_e32 v18, 0xb102e308, v16
	v_pk_add_f32 v[16:17], v[20:21], v[18:19]
	v_ldexp_f32 v5, v5, 1
	v_sub_f32_e32 v7, v17, v19
	v_sub_f32_e32 v7, v21, v7
	v_add_f32_e32 v23, v5, v7
	v_mov_b32_e32 v22, v20
	v_pk_add_f32 v[20:21], v[16:17], v[20:21] neg_lo:[0,1] neg_hi:[0,1]
	v_pk_add_f32 v[24:25], v[16:17], v[22:23]
	v_mov_b32_e32 v19, v16
	v_mov_b32_e32 v21, v25
	v_pk_add_f32 v[84:85], v[18:19], v[20:21] neg_lo:[0,1] neg_hi:[0,1]
	v_pk_add_f32 v[18:19], v[18:19], v[20:21]
	v_mov_b32_e32 v22, v23
	v_pk_add_f32 v[20:21], v[18:19], v[16:17] op_sel:[1,0] op_sel_hi:[0,1] neg_lo:[0,1] neg_hi:[0,1]
	v_pk_add_f32 v[86:87], v[24:25], v[20:21] op_sel_hi:[1,0] neg_lo:[0,1] neg_hi:[0,1]
	v_mov_b32_e32 v24, v25
	v_mov_b32_e32 v25, v19
	v_pk_mov_b32 v[20:21], v[16:17], v[20:21] op_sel:[1,0]
	v_mov_b32_e32 v23, v16
	v_pk_add_f32 v[20:21], v[24:25], v[20:21] neg_lo:[0,1] neg_hi:[0,1]
	v_mov_b32_e32 v86, v84
	v_pk_add_f32 v[16:17], v[22:23], v[20:21] neg_lo:[0,1] neg_hi:[0,1]
	v_mov_b32_e32 v85, v19
	v_pk_add_f32 v[20:21], v[86:87], v[16:17]
	s_nop 0
	v_pk_add_f32 v[22:23], v[20:21], v[20:21] op_sel:[0,1] op_sel_hi:[1,0]
	s_nop 0
	v_pk_add_f32 v[18:19], v[18:19], v[22:23] op_sel:[1,0] op_sel_hi:[0,1]
	v_mov_b32_e32 v21, v18
	v_pk_add_f32 v[24:25], v[20:21], v[84:85] neg_lo:[0,1] neg_hi:[0,1]
	v_mov_b32_e32 v17, v22
	v_sub_f32_e32 v5, v20, v24
	v_pk_add_f32 v[16:17], v[16:17], v[24:25] neg_lo:[0,1] neg_hi:[0,1]
	v_sub_f32_e32 v5, v84, v5
	v_add_f32_e32 v5, v16, v5
	v_add_f32_e32 v5, v5, v17
	v_add_f32_e32 v5, v18, v5
	v_cndmask_b32_e32 v5, v153, v5, vcc
	v_cmp_ngt_f32_e32 vcc, -1.0, v1
	s_nop 1
	v_cndmask_b32_e32 v5, v154, v5, vcc
	v_cmp_neq_f32_e32 vcc, -1.0, v1
	s_nop 1
	v_cndmask_b32_e32 v5, v155, v5, vcc
	v_cmp_lt_f32_e64 vcc, |v1|, s50
	s_nop 1
	v_cndmask_b32_e32 v1, v5, v1, vcc
	v_sub_f32_e32 v3, v3, v1
	v_mov_b32_e32 v1, v83
	v_pk_add_f32 v[84:85], v[0:1], v[2:3]
	v_and_b32_e32 v2, 0xffffffc0, v36
	v_sub_f32_e32 v87, v84, v85
	v_max3_f32 v35, v6, v4, v87
	v_sub_f32_e32 v0, v6, v35
	v_mul_f32_e32 v0, 0x3fb8aa3b, v0
	v_exp_f32_e32 v86, v0
	v_sub_f32_e32 v0, v26, v35
	v_mul_f32_e32 v0, 0x3fb8aa3b, v0
	v_exp_f32_e32 v22, v0
	v_sub_f32_e32 v0, v27, v35
	v_mul_f32_e32 v0, 0x3fb8aa3b, v0
	v_exp_f32_e32 v23, v0
	v_sub_f32_e32 v0, v28, v35
	v_mul_f32_e32 v0, 0x3fb8aa3b, v0
	v_exp_f32_e32 v20, v0
	v_sub_f32_e32 v0, v29, v35
	v_mul_f32_e32 v0, 0x3fb8aa3b, v0
	v_exp_f32_e32 v21, v0
	v_sub_f32_e32 v0, v30, v35
	v_mul_f32_e32 v0, 0x3fb8aa3b, v0
	v_exp_f32_e32 v18, v0
	v_sub_f32_e32 v0, v31, v35
	v_mul_f32_e32 v0, 0x3fb8aa3b, v0
	v_exp_f32_e32 v19, v0
	v_sub_f32_e32 v0, v32, v35
	v_mul_f32_e32 v0, 0x3fb8aa3b, v0
	v_exp_f32_e32 v16, v0
	v_sub_f32_e32 v0, v87, v35
	v_mul_f32_e32 v0, 0x3fb8aa3b, v0
	v_exp_f32_e32 v17, v0
	v_bfe_u32 v0, v36, 3, 3
	v_add_u32_e32 v0, v38, v0
	v_ashrrev_i32_e32 v1, 31, v0
	v_lshlrev_b64 v[0:1], 12, v[0:1]
	v_ashrrev_i32_e32 v3, 31, v2
	v_lshl_add_u64 v[0:1], s[36:37], 0, v[0:1]
	v_lshlrev_b64 v[2:3], 1, v[2:3]
	v_lshl_add_u64 v[0:1], v[0:1], 0, v[2:3]
	flat_load_dwordx4 v[92:95], v[0:1]
	v_add_u32_e32 v4, v38, v90
	v_ashrrev_i32_e32 v5, 31, v4
	v_lshlrev_b64 v[4:5], 12, v[4:5]
	v_lshl_add_u64 v[4:5], s[38:39], 0, v[4:5]
	v_lshl_add_u64 v[4:5], v[4:5], 0, v[2:3]
	v_pk_mul_f32 v[16:17], v[16:17], s[44:45] op_sel_hi:[1,0]
	v_and_b32_e32 v84, 63, v36
	global_load_dwordx4 v[102:105], v[4:5], off
	global_load_dwordx4 v[106:109], v[0:1], off offset:16
	global_load_dwordx4 v[110:113], v[4:5], off offset:16
	global_load_dwordx4 v[114:117], v[0:1], off offset:32
	global_load_dwordx4 v[118:121], v[4:5], off offset:32
	global_load_dwordx4 v[122:125], v[0:1], off offset:48
	global_load_dwordx4 v[126:129], v[4:5], off offset:48
	global_load_dwordx4 v[130:133], v[0:1], off offset:64
	global_load_dwordx4 v[134:137], v[4:5], off offset:64
	global_load_dwordx4 v[138:141], v[0:1], off offset:80
	global_load_dwordx4 v[142:145], v[4:5], off offset:80
	global_load_dwordx4 v[158:161], v[0:1], off offset:96
	global_load_dwordx4 v[162:165], v[4:5], off offset:96
	s_waitcnt vmcnt(0) lgkmcnt(0)
	v_lshlrev_b32_e32 v2, 16, v92
	v_and_b32_e32 v3, 0xffff0000, v92
	v_lshlrev_b32_e32 v6, 16, v93
	v_and_b32_e32 v7, 0xffff0000, v93
	v_lshlrev_b32_e32 v15, 16, v94
	v_and_b32_e32 v24, 0xffff0000, v94
	v_lshlrev_b32_e32 v25, 16, v95
	v_and_b32_e32 v37, 0xffff0000, v95
	v_mov_b64_e32 v[92:93], v[102:103]
	v_mov_b64_e32 v[94:95], v[104:105]
	s_waitcnt vmcnt(0) lgkmcnt(0)
	v_lshlrev_b32_e32 v88, 16, v92
	v_and_b32_e32 v89, 0xffff0000, v92
	v_fma_f32 v2, v2, v88, 0
	v_lshlrev_b32_e32 v91, 16, v93
	v_fmac_f32_e32 v2, v3, v89
	v_and_b32_e32 v92, 0xffff0000, v93
	v_fmac_f32_e32 v2, v6, v91
	v_lshlrev_b32_e32 v93, 16, v94
	v_fmac_f32_e32 v2, v7, v92
	v_and_b32_e32 v94, 0xffff0000, v94
	v_fmac_f32_e32 v2, v15, v93
	v_lshlrev_b32_e32 v96, 16, v95
	v_fmac_f32_e32 v2, v24, v94
	v_and_b32_e32 v95, 0xffff0000, v95
	v_fmac_f32_e32 v2, v25, v96
	v_fmac_f32_e32 v2, v37, v95
	v_mov_b64_e32 v[92:93], v[106:107]
	v_mov_b64_e32 v[94:95], v[108:109]
	s_waitcnt vmcnt(0) lgkmcnt(0)
	v_lshlrev_b32_e32 v3, 16, v92
	v_and_b32_e32 v6, 0xffff0000, v92
	v_lshlrev_b32_e32 v7, 16, v93
	v_and_b32_e32 v15, 0xffff0000, v93
	v_lshlrev_b32_e32 v24, 16, v94
	v_and_b32_e32 v25, 0xffff0000, v94
	v_lshlrev_b32_e32 v37, 16, v95
	v_and_b32_e32 v88, 0xffff0000, v95
	v_mov_b64_e32 v[92:93], v[110:111]
	v_mov_b64_e32 v[94:95], v[112:113]
	s_waitcnt vmcnt(0) lgkmcnt(0)
	v_lshlrev_b32_e32 v89, 16, v92
	v_and_b32_e32 v91, 0xffff0000, v92
	v_fmac_f32_e32 v2, v3, v89
	v_lshlrev_b32_e32 v92, 16, v93
	v_fmac_f32_e32 v2, v6, v91
	v_and_b32_e32 v93, 0xffff0000, v93
	v_fmac_f32_e32 v2, v7, v92
	v_lshlrev_b32_e32 v96, 16, v94
	v_fmac_f32_e32 v2, v15, v93
	v_and_b32_e32 v94, 0xffff0000, v94
	v_fmac_f32_e32 v2, v24, v96
	v_lshlrev_b32_e32 v97, 16, v95
	v_fmac_f32_e32 v2, v25, v94
	v_and_b32_e32 v95, 0xffff0000, v95
	v_fmac_f32_e32 v2, v37, v97
	v_fmac_f32_e32 v2, v88, v95
	v_mov_b64_e32 v[92:93], v[114:115]
	v_mov_b64_e32 v[94:95], v[116:117]
	s_waitcnt vmcnt(0) lgkmcnt(0)
	v_lshlrev_b32_e32 v3, 16, v92
	v_and_b32_e32 v6, 0xffff0000, v92
	v_lshlrev_b32_e32 v7, 16, v93
	v_and_b32_e32 v15, 0xffff0000, v93
	v_lshlrev_b32_e32 v24, 16, v94
	v_and_b32_e32 v25, 0xffff0000, v94
	v_lshlrev_b32_e32 v37, 16, v95
	v_and_b32_e32 v88, 0xffff0000, v95
	v_mov_b64_e32 v[92:93], v[118:119]
	v_mov_b64_e32 v[94:95], v[120:121]
	s_waitcnt vmcnt(0) lgkmcnt(0)
	v_lshlrev_b32_e32 v89, 16, v92
	v_and_b32_e32 v91, 0xffff0000, v92
	v_fmac_f32_e32 v2, v3, v89
	v_lshlrev_b32_e32 v92, 16, v93
	v_fmac_f32_e32 v2, v6, v91
	v_and_b32_e32 v93, 0xffff0000, v93
	v_fmac_f32_e32 v2, v7, v92
	v_lshlrev_b32_e32 v96, 16, v94
	v_fmac_f32_e32 v2, v15, v93
	v_and_b32_e32 v94, 0xffff0000, v94
	v_fmac_f32_e32 v2, v24, v96
	v_lshlrev_b32_e32 v97, 16, v95
	v_fmac_f32_e32 v2, v25, v94
	v_and_b32_e32 v95, 0xffff0000, v95
	v_fmac_f32_e32 v2, v37, v97
	v_fmac_f32_e32 v2, v88, v95
	v_mov_b64_e32 v[92:93], v[122:123]
	v_mov_b64_e32 v[94:95], v[124:125]
	s_waitcnt vmcnt(0) lgkmcnt(0)
	v_lshlrev_b32_e32 v3, 16, v92
	v_and_b32_e32 v6, 0xffff0000, v92
	v_lshlrev_b32_e32 v7, 16, v93
	v_and_b32_e32 v15, 0xffff0000, v93
	v_lshlrev_b32_e32 v24, 16, v94
	v_and_b32_e32 v25, 0xffff0000, v94
	v_lshlrev_b32_e32 v37, 16, v95
	v_and_b32_e32 v88, 0xffff0000, v95
	v_mov_b64_e32 v[92:93], v[126:127]
	v_mov_b64_e32 v[94:95], v[128:129]
	s_waitcnt vmcnt(0) lgkmcnt(0)
	v_lshlrev_b32_e32 v89, 16, v92
	v_and_b32_e32 v91, 0xffff0000, v92
	v_fmac_f32_e32 v2, v3, v89
	v_lshlrev_b32_e32 v92, 16, v93
	v_fmac_f32_e32 v2, v6, v91
	v_and_b32_e32 v93, 0xffff0000, v93
	v_fmac_f32_e32 v2, v7, v92
	v_lshlrev_b32_e32 v96, 16, v94
	v_fmac_f32_e32 v2, v15, v93
	v_and_b32_e32 v94, 0xffff0000, v94
	v_fmac_f32_e32 v2, v24, v96
	v_lshlrev_b32_e32 v97, 16, v95
	v_fmac_f32_e32 v2, v25, v94
	v_and_b32_e32 v95, 0xffff0000, v95
	v_fmac_f32_e32 v2, v37, v97
	v_fmac_f32_e32 v2, v88, v95
	v_mov_b64_e32 v[92:93], v[130:131]
	v_mov_b64_e32 v[94:95], v[132:133]
	s_waitcnt vmcnt(0) lgkmcnt(0)
	v_lshlrev_b32_e32 v3, 16, v92
	v_and_b32_e32 v6, 0xffff0000, v92
	v_lshlrev_b32_e32 v7, 16, v93
	v_and_b32_e32 v15, 0xffff0000, v93
	v_lshlrev_b32_e32 v24, 16, v94
	v_and_b32_e32 v25, 0xffff0000, v94
	v_lshlrev_b32_e32 v37, 16, v95
	v_and_b32_e32 v88, 0xffff0000, v95
	v_mov_b64_e32 v[92:93], v[134:135]
	v_mov_b64_e32 v[94:95], v[136:137]
	s_waitcnt vmcnt(0) lgkmcnt(0)
	v_lshlrev_b32_e32 v89, 16, v92
	v_and_b32_e32 v91, 0xffff0000, v92
	v_fmac_f32_e32 v2, v3, v89
	v_lshlrev_b32_e32 v92, 16, v93
	v_fmac_f32_e32 v2, v6, v91
	v_and_b32_e32 v93, 0xffff0000, v93
	v_fmac_f32_e32 v2, v7, v92
	v_lshlrev_b32_e32 v96, 16, v94
	v_fmac_f32_e32 v2, v15, v93
	v_and_b32_e32 v94, 0xffff0000, v94
	v_fmac_f32_e32 v2, v24, v96
	v_lshlrev_b32_e32 v97, 16, v95
	v_fmac_f32_e32 v2, v25, v94
	v_and_b32_e32 v95, 0xffff0000, v95
	v_fmac_f32_e32 v2, v37, v97
	v_fmac_f32_e32 v2, v88, v95
	v_mov_b64_e32 v[92:93], v[138:139]
	v_mov_b64_e32 v[94:95], v[140:141]
	s_waitcnt vmcnt(0) lgkmcnt(0)
	v_lshlrev_b32_e32 v3, 16, v92
	v_and_b32_e32 v6, 0xffff0000, v92
	v_lshlrev_b32_e32 v7, 16, v93
	v_and_b32_e32 v15, 0xffff0000, v93
	v_lshlrev_b32_e32 v24, 16, v94
	v_and_b32_e32 v25, 0xffff0000, v94
	v_lshlrev_b32_e32 v37, 16, v95
	v_and_b32_e32 v88, 0xffff0000, v95
	v_mov_b64_e32 v[92:93], v[142:143]
	v_mov_b64_e32 v[94:95], v[144:145]
	s_waitcnt vmcnt(0) lgkmcnt(0)
	v_lshlrev_b32_e32 v89, 16, v92
	v_and_b32_e32 v91, 0xffff0000, v92
	v_fmac_f32_e32 v2, v3, v89
	v_lshlrev_b32_e32 v92, 16, v93
	v_fmac_f32_e32 v2, v6, v91
	v_and_b32_e32 v93, 0xffff0000, v93
	v_fmac_f32_e32 v2, v7, v92
	v_lshlrev_b32_e32 v96, 16, v94
	v_fmac_f32_e32 v2, v15, v93
	v_and_b32_e32 v94, 0xffff0000, v94
	v_fmac_f32_e32 v2, v24, v96
	v_lshlrev_b32_e32 v97, 16, v95
	v_fmac_f32_e32 v2, v25, v94
	v_and_b32_e32 v95, 0xffff0000, v95
	v_fmac_f32_e32 v2, v37, v97
	v_fmac_f32_e32 v2, v88, v95
	v_mov_b64_e32 v[92:93], v[158:159]
	v_mov_b64_e32 v[94:95], v[160:161]
	v_mov_b64_e32 v[96:97], v[162:163]
	v_mov_b64_e32 v[98:99], v[164:165]
	s_waitcnt vmcnt(0) lgkmcnt(0)
	v_lshlrev_b32_e32 v3, 16, v92
	v_lshlrev_b32_e32 v24, 16, v96
	v_and_b32_e32 v6, 0xffff0000, v92
	v_and_b32_e32 v25, 0xffff0000, v96
	v_fmac_f32_e32 v2, v3, v24
	v_lshlrev_b32_e32 v7, 16, v93
	v_lshlrev_b32_e32 v37, 16, v97
	v_fmac_f32_e32 v2, v6, v25
	v_and_b32_e32 v15, 0xffff0000, v93
	v_and_b32_e32 v88, 0xffff0000, v97
	v_fmac_f32_e32 v2, v7, v37
	v_and_b32_e32 v6, 0xffff0000, v94
	v_lshlrev_b32_e32 v7, 16, v94
	v_and_b32_e32 v24, 0xffff0000, v98
	v_lshlrev_b32_e32 v25, 16, v98
	v_fmac_f32_e32 v2, v15, v88
	v_pk_mul_f32 v[6:7], v[6:7], v[24:25]
	v_lshlrev_b32_e32 v3, 16, v95
	v_add_f32_e32 v2, v7, v2
	v_add_f32_e32 v15, v6, v2
	v_and_b32_e32 v2, 0xffff0000, v95
	v_and_b32_e32 v6, 0xffff0000, v99
	v_lshlrev_b32_e32 v7, 16, v99
	v_pk_mul_f32 v[2:3], v[2:3], v[6:7]
	v_ashrrev_i32_e32 v37, 31, v36
	v_add_f32_e32 v3, v3, v15
	v_add_f32_e32 v15, v2, v3
	flat_load_dwordx4 v[0:3], v[0:1] offset:112
	s_nop 0
	flat_load_dwordx4 v[4:7], v[4:5] offset:112
	s_waitcnt vmcnt(0) lgkmcnt(0)
	v_and_b32_e32 v24, 0xffff0000, v0
	v_lshlrev_b32_e32 v25, 16, v0
	v_and_b32_e32 v88, 0xffff0000, v4
	v_lshlrev_b32_e32 v89, 16, v4
	v_pk_mul_f32 v[24:25], v[24:25], v[88:89]
	v_and_b32_e32 v4, 0xffff0000, v5
	v_add_f32_e32 v0, v25, v15
	v_add_f32_e32 v15, v24, v0
	v_and_b32_e32 v0, 0xffff0000, v1
	v_lshlrev_b32_e32 v1, 16, v1
	v_lshlrev_b32_e32 v5, 16, v5
	v_pk_mul_f32 v[0:1], v[0:1], v[4:5]
	v_and_b32_e32 v4, 0xffff0000, v6
	v_add_f32_e32 v1, v1, v15
	v_add_f32_e32 v15, v0, v1
	v_and_b32_e32 v0, 0xffff0000, v2
	v_lshlrev_b32_e32 v1, 16, v2
	v_lshlrev_b32_e32 v5, 16, v6
	v_pk_mul_f32 v[0:1], v[0:1], v[4:5]
	v_and_b32_e32 v2, 0xffff0000, v7
	v_add_f32_e32 v1, v1, v15
	v_add_f32_e32 v4, v0, v1
	v_and_b32_e32 v0, 0xffff0000, v3
	v_lshlrev_b32_e32 v1, 16, v3
	v_lshlrev_b32_e32 v3, 16, v7
	v_pk_mul_f32 v[0:1], v[0:1], v[2:3]
	v_lshlrev_b64 v[24:25], 2, v[36:37]
	v_add_f32_e32 v1, v1, v4
	v_add_f32_e32 v0, v0, v1
	v_lshl_add_u32 v1, v36, 2, 0
	v_add_u32_e32 v91, 0x18000, v1
	ds_write_b32 v91, v0
	v_lshl_add_u64 v[0:1], s[48:49], 0, v[24:25]
	flat_load_dword v92, v[0:1]
	v_lshl_add_u64 v[88:89], v[36:37], 0, s[30:31]
	v_lshlrev_b64 v[0:1], 11, v[38:39]
	v_lshl_add_u64 v[0:1], v[0:1], 0, v[88:89]
	v_lshlrev_b64 v[0:1], 1, v[0:1]
	v_mov_b32_e32 v166, v0
	global_load_ushort v170, v166, s[28:29]
	global_load_ushort v178, v166, s[24:25]
	v_add_u32_e32 v166, 0x1000, v166
	global_load_ushort v171, v166, s[28:29]
	global_load_ushort v179, v166, s[24:25]
	v_add_u32_e32 v166, 0x1000, v166
	global_load_ushort v172, v166, s[28:29]
	global_load_ushort v180, v166, s[24:25]
	v_add_u32_e32 v166, 0x1000, v166
	global_load_ushort v173, v166, s[28:29]
	global_load_ushort v181, v166, s[24:25]
	v_add_u32_e32 v166, 0x1000, v166
	global_load_ushort v174, v166, s[28:29]
	global_load_ushort v182, v166, s[24:25]
	v_add_u32_e32 v166, 0x1000, v166
	global_load_ushort v175, v166, s[28:29]
	global_load_ushort v183, v166, s[24:25]
	v_add_u32_e32 v166, 0x1000, v166
	global_load_ushort v176, v166, s[28:29]
	global_load_ushort v184, v166, s[24:25]
	v_add_u32_e32 v166, 0x1000, v166
	global_load_ushort v177, v166, s[28:29]
	global_load_ushort v185, v166, s[24:25]
	v_lshl_add_u64 v[2:3], s[28:29], 0, v[0:1]
	v_lshl_add_u64 v[4:5], s[24:25], 0, v[0:1]
	v_lshlrev_b64 v[0:1], 11, v[46:47]
	v_lshl_add_u64 v[0:1], v[0:1], 0, v[88:89]
	v_lshlrev_b64 v[6:7], 1, v[0:1]
	v_lshl_add_u64 v[0:1], s[28:29], 0, v[6:7]
	s_waitcnt vmcnt(0)
	v_mov_b32_e32 v2, v170
	s_nop 0
	v_mov_b32_e32 v0, v171
	s_waitcnt vmcnt(0) lgkmcnt(0)
	v_lshlrev_b32_e32 v1, 16, v0
	v_lshlrev_b32_e32 v0, 16, v2
	v_lshl_add_u64 v[2:3], s[24:25], 0, v[6:7]
	v_mov_b32_e32 v4, v178
	s_nop 0
	v_mov_b32_e32 v2, v179
	v_pk_mul_f32 v[6:7], v[22:23], s[44:45] op_sel_hi:[1,0]
	v_pk_mul_f32 v[0:1], v[8:9], v[0:1]
	s_waitcnt vmcnt(0) lgkmcnt(0)
	v_lshlrev_b32_e32 v3, 16, v2
	v_lshlrev_b32_e32 v2, 16, v4
	v_pk_mul_f32 v[8:9], v[6:7], v[2:3]
	s_nop 0
	v_add_f32_e32 v2, 0, v8
	v_add_f32_e32 v15, v9, v2
	v_lshlrev_b64 v[2:3], 11, v[50:51]
	v_lshl_add_u64 v[2:3], v[2:3], 0, v[88:89]
	v_lshlrev_b64 v[2:3], 1, v[2:3]
	v_lshl_add_u64 v[4:5], s[28:29], 0, v[2:3]
	v_lshl_add_u64 v[6:7], s[24:25], 0, v[2:3]
	v_lshlrev_b64 v[2:3], 11, v[56:57]
	v_lshl_add_u64 v[2:3], v[2:3], 0, v[88:89]
	v_lshlrev_b64 v[22:23], 1, v[2:3]
	v_lshl_add_u64 v[2:3], s[28:29], 0, v[22:23]
	v_mov_b32_e32 v4, v172
	s_nop 0
	v_mov_b32_e32 v2, v173
	s_waitcnt vmcnt(0) lgkmcnt(0)
	v_lshlrev_b32_e32 v3, 16, v2
	v_lshlrev_b32_e32 v2, 16, v4
	v_lshl_add_u64 v[4:5], s[24:25], 0, v[22:23]
	v_mov_b32_e32 v6, v180
	s_nop 0
	v_mov_b32_e32 v4, v181
	v_pk_mul_f32 v[2:3], v[10:11], v[2:3]
	v_pk_mul_f32 v[10:11], v[20:21], s[44:45] op_sel_hi:[1,0]
	s_waitcnt vmcnt(0) lgkmcnt(0)
	v_lshlrev_b32_e32 v5, 16, v4
	v_lshlrev_b32_e32 v4, 16, v6
	v_pk_mul_f32 v[10:11], v[10:11], v[4:5]
	s_nop 0
	v_add_f32_e32 v4, v10, v15
	v_add_f32_e32 v15, v11, v4
	v_lshlrev_b64 v[4:5], 11, v[62:63]
	v_lshl_add_u64 v[4:5], v[4:5], 0, v[88:89]
	v_lshlrev_b64 v[4:5], 1, v[4:5]
	v_lshl_add_u64 v[6:7], s[28:29], 0, v[4:5]
	v_lshl_add_u64 v[20:21], s[24:25], 0, v[4:5]
	v_lshlrev_b64 v[4:5], 11, v[70:71]
	v_lshl_add_u64 v[4:5], v[4:5], 0, v[88:89]
	v_lshlrev_b64 v[22:23], 1, v[4:5]
	v_lshl_add_u64 v[4:5], s[28:29], 0, v[22:23]
	v_mov_b32_e32 v6, v174
	s_nop 0
	v_mov_b32_e32 v4, v175
	s_waitcnt vmcnt(0) lgkmcnt(0)
	v_lshlrev_b32_e32 v5, 16, v4
	v_lshlrev_b32_e32 v4, 16, v6
	v_lshl_add_u64 v[6:7], s[24:25], 0, v[22:23]
	v_pk_mul_f32 v[4:5], v[12:13], v[4:5]
	v_pk_mul_f32 v[12:13], v[18:19], s[44:45] op_sel_hi:[1,0]
	v_mov_b32_e32 v18, v182
	s_nop 0
	v_mov_b32_e32 v6, v183
	s_waitcnt vmcnt(0) lgkmcnt(0)
	v_lshlrev_b32_e32 v7, 16, v6
	v_lshlrev_b32_e32 v6, 16, v18
	v_pk_mul_f32 v[12:13], v[12:13], v[6:7]
	s_nop 0
	v_add_f32_e32 v6, v12, v15
	v_add_f32_e32 v93, v13, v6
	v_lshlrev_b64 v[6:7], 11, v[74:75]
	v_lshl_add_u64 v[6:7], v[6:7], 0, v[88:89]
	v_lshlrev_b64 v[6:7], 1, v[6:7]
	v_lshl_add_u64 v[18:19], s[28:29], 0, v[6:7]
	v_lshl_add_u64 v[20:21], s[24:25], 0, v[6:7]
	v_lshlrev_b64 v[6:7], 11, v[80:81]
	v_lshl_add_u64 v[6:7], v[6:7], 0, v[88:89]
	v_lshlrev_b64 v[22:23], 1, v[6:7]
	v_lshl_add_u64 v[6:7], s[28:29], 0, v[22:23]
	v_mov_b32_e32 v15, v176
	s_nop 0
	v_mov_b32_e32 v6, v177
	s_waitcnt vmcnt(0) lgkmcnt(0)
	v_lshlrev_b32_e32 v7, 16, v6
	v_lshlrev_b32_e32 v6, 16, v15
	v_mov_b32_e32 v15, v86
	v_pk_mul_f32 v[6:7], v[14:15], v[6:7]
	v_lshl_add_u64 v[14:15], s[24:25], 0, v[22:23]
	v_mov_b32_e32 v18, v184
	s_nop 0
	v_mov_b32_e32 v14, v185
	s_waitcnt vmcnt(0) lgkmcnt(0)
	v_lshlrev_b32_e32 v15, 16, v14
	v_lshlrev_b32_e32 v14, 16, v18
	v_pk_mul_f32 v[14:15], v[16:17], v[14:15]
	v_lshl_add_u32 v17, v36, 5, 0
	v_add_f32_e32 v16, v14, v93
	ds_write_b128 v17, v[0:3]
	ds_write_b128 v17, v[4:7] offset:16
	ds_write_b128 v17, v[8:11] offset:16384
	ds_write_b128 v17, v[12:15] offset:16400
	v_lshl_add_u64 v[8:9], s[6:7], 0, v[24:25]
	s_mov_b32 s6, 0x26960000
	v_add_f32_e32 v16, v15, v16
	v_add_co_u32_e32 v8, vcc, s6, v8
	v_fmac_f32_e32 v16, v92, v86
	s_nop 0
	v_addc_co_u32_e32 v9, vcc, 0, v9, vcc
	flat_store_dword v[8:9], v16
	v_mul_f32_e32 v9, v92, v0
	ds_bpermute_b32 v9, v146, v9
	v_cmp_eq_u32_e64 s[6:7], 0, v84
	v_ashrrev_i32_e32 v8, 1, v36
	s_waitcnt lgkmcnt(0)
	v_fmac_f32_e32 v9, v92, v0
	ds_bpermute_b32 v0, v147, v9
	s_waitcnt lgkmcnt(0)
	v_add_f32_e32 v0, v9, v0
	ds_bpermute_b32 v9, v148, v0
	s_waitcnt lgkmcnt(0)
	v_add_f32_e32 v0, v0, v9
	ds_bpermute_b32 v9, v149, v0
	s_waitcnt lgkmcnt(0)
	v_add_f32_e32 v0, v0, v9
	ds_bpermute_b32 v9, v150, v0
	s_waitcnt lgkmcnt(0)
	v_add_f32_e32 v0, v0, v9
	ds_bpermute_b32 v9, v151, v0
	s_and_saveexec_b64 s[48:49], s[6:7]
	s_cbranch_execz .LBB0_819
	s_waitcnt lgkmcnt(0)
	v_add_f32_e32 v0, v0, v9
	v_add_u32_e32 v9, 0, v8
	v_add_u32_e32 v9, 0x18900, v9
	ds_write_b32 v9, v0

.LBB0_921:
	s_lshl_b32 s6, s34, 1
	s_and_b32 s6, s6, -8
	v_mov_b32_e32 v36, v201
	v_mov_b32_e32 v2, 0
	s_addk_i32 s6, 0x4000
	s_and_b32 s38, s34, 3
	v_add_u32_e32 v40, s6, v2
	v_add_u32_e32 v0, s34, v2
	v_readlane_b32 s6, v255, 12
	v_ashrrev_i32_e32 v1, 31, v0
	v_readlane_b32 s7, v255, 13
	v_readlane_b32 s36, v255, 10
	v_readlane_b32 s37, v255, 11
	v_lshl_add_u64 v[0:1], v[0:1], 2, s[6:7]
	flat_load_dword v6, v[0:1]
	s_lshl_b32 s6, s38, 2
	v_readlane_b32 s7, v255, 14
	v_add_u32_e32 v0, s38, v2
	s_add_u32 s6, s7, s6
	v_readlane_b32 s7, v255, 15
	v_ashrrev_i32_e32 v1, 31, v0
	v_ashrrev_i32_e32 v41, 31, v40
	v_ashrrev_i32_e32 v3, 31, v2
	s_addc_u32 s7, s7, 0
	v_lshl_add_u64 v[4:5], v[0:1], 2, s[36:37]
	v_lshlrev_b64 v[38:39], 5, v[40:41]
	flat_load_dword v0, v[4:5]
	flat_load_dword v7, v[4:5] offset:16
	v_lshl_add_u64 v[4:5], s[6:7], 0, v[38:39]
	v_lshlrev_b64 v[2:3], 2, v[2:3]
	v_lshl_add_u64 v[4:5], v[4:5], 0, v[2:3]
	flat_load_dword v32, v[4:5]
	flat_load_dword v1, v[4:5] offset:16
	flat_load_dword v186, v[4:5] offset:32
	flat_load_dword v187, v[4:5] offset:48
	flat_load_dword v188, v[4:5] offset:64
	flat_load_dword v189, v[4:5] offset:80
	flat_load_dword v190, v[4:5] offset:96
	flat_load_dword v191, v[4:5] offset:112
	flat_load_dword v192, v[4:5] offset:128
	flat_load_dword v193, v[4:5] offset:144
	flat_load_dword v194, v[4:5] offset:160
	flat_load_dword v195, v[4:5] offset:176
	flat_load_dword v196, v[4:5] offset:192
	flat_load_dword v197, v[4:5] offset:208
	flat_load_dword v198, v[4:5] offset:224
	flat_load_dword v199, v[4:5] offset:240
	v_add_u32_e32 v44, 1, v40
	v_ashrrev_i32_e32 v45, 31, v44
	v_lshlrev_b64 v[42:43], 5, v[44:45]
	v_add_u32_e32 v48, 2, v40
	v_ashrrev_i32_e32 v49, 31, v48
	v_lshlrev_b64 v[46:47], 5, v[48:49]
	v_add_u32_e32 v56, 3, v40
	v_ashrrev_i32_e32 v57, 31, v56
	v_lshlrev_b64 v[54:55], 5, v[56:57]
	v_add_u32_e32 v62, 4, v40
	v_ashrrev_i32_e32 v63, 31, v62
	v_lshlrev_b64 v[60:61], 5, v[62:63]
	v_add_u32_e32 v70, 5, v40
	v_ashrrev_i32_e32 v71, 31, v70
	v_lshlrev_b64 v[64:65], 5, v[70:71]
	v_and_b32_e32 v90, 7, v36
	s_ashr_i32 s35, s34, 31
	s_lshl_b32 s28, s38, 9
	s_waitcnt vmcnt(0) lgkmcnt(0)
	v_add_f32_e32 v1, v7, v1
	v_min_f32_e32 v20, 0, v1
	v_mul_f32_e64 v1, |v1|, s45
	v_exp_f32_e32 v1, v1
	s_nop 0
	v_add_f32_e32 v8, 1.0, v1
	v_add_f32_e32 v4, -1.0, v8
	v_sub_f32_e32 v5, v4, v8
	v_add_f32_e32 v5, 1.0, v5
	v_sub_f32_e32 v4, v1, v4
	v_add_f32_e32 v9, v4, v5
	v_frexp_mant_f32_e32 v4, v8
	v_cmp_gt_f32_e32 vcc, s46, v4
	v_cvt_f64_f32_e32 v[4:5], v8
	v_frexp_exp_i32_f64_e32 v4, v[4:5]
	v_subbrev_co_u32_e32 v14, vcc, 0, v4, vcc
	v_sub_u32_e32 v4, 0, v14
	v_ldexp_f32 v5, v8, v4
	v_add_f32_e32 v8, -1.0, v5
	v_add_f32_e32 v10, 1.0, v5
	v_ldexp_f32 v4, v9, v4
	v_add_f32_e32 v9, 1.0, v8
	v_add_f32_e32 v11, -1.0, v10
	v_sub_f32_e32 v9, v5, v9
	v_sub_f32_e32 v5, v5, v11
	v_add_f32_e32 v9, v4, v9
	v_add_f32_e32 v4, v4, v5
	v_add_f32_e32 v15, v10, v4
	v_rcp_f32_e32 v17, v15
	v_sub_f32_e32 v5, v15, v10
	v_sub_f32_e32 v16, v4, v5
	v_add_f32_e32 v5, v8, v9
	v_mul_f32_e32 v19, v5, v17
	v_sub_f32_e32 v4, v5, v8
	v_mul_f32_e32 v8, v15, v19
	v_fma_f32 v10, v19, v15, -v8
	v_fmac_f32_e32 v10, v19, v16
	v_sub_f32_e32 v18, v9, v4
	v_add_f32_e32 v4, v8, v10
	v_sub_f32_e32 v9, v5, v4
	v_pk_add_f32 v[12:13], v[4:5], v[8:9] neg_lo:[0,1] neg_hi:[0,1]
	v_mov_b32_e32 v11, v4
	v_pk_add_f32 v[4:5], v[12:13], v[10:11] neg_lo:[0,1] neg_hi:[0,1]
	v_cmp_neq_f32_e32 vcc, s48, v1
	v_add_f32_e32 v5, v18, v5
	v_add_f32_e32 v4, v4, v5
	v_add_f32_e32 v5, v9, v4
	v_mul_f32_e32 v18, v17, v5
	v_mul_f32_e32 v8, v15, v18
	v_fma_f32 v10, v18, v15, -v8
	v_fmac_f32_e32 v10, v18, v16
	v_sub_f32_e32 v9, v9, v5
	v_add_f32_e32 v15, v4, v9
	v_add_f32_e32 v4, v8, v10
	v_sub_f32_e32 v9, v5, v4
	v_pk_add_f32 v[12:13], v[4:5], v[8:9] neg_lo:[0,1] neg_hi:[0,1]
	v_mov_b32_e32 v11, v4
	v_pk_add_f32 v[4:5], v[12:13], v[10:11] neg_lo:[0,1] neg_hi:[0,1]
	s_nop 0
	v_add_f32_e32 v5, v15, v5
	v_add_f32_e32 v4, v4, v5
	v_add_f32_e32 v5, v19, v18
	v_add_f32_e32 v4, v9, v4
	v_sub_f32_e32 v8, v5, v19
	v_mul_f32_e32 v4, v17, v4
	v_sub_f32_e32 v8, v18, v8
	v_add_f32_e32 v8, v8, v4
	v_add_f32_e32 v10, v5, v8
	v_mul_f32_e32 v11, v10, v10
	v_fmamk_f32 v4, v11, 0x3e9b6dac, v152
	v_fmaak_f32 v35, v11, v4, 0x3f2aaada
	v_cvt_f32_i32_e32 v4, v14
	v_sub_f32_e32 v5, v10, v5
	v_sub_f32_e32 v5, v8, v5
	v_ldexp_f32 v12, v5, 1
	v_mul_f32_e32 v5, v10, v11
	v_ldexp_f32 v9, v10, 1
	v_pk_mul_f32 v[10:11], v[4:5], v[34:35]
	s_nop 0
	v_fma_f32 v8, v4, s47, -v10
	v_fmac_f32_e32 v8, 0xb102e308, v4
	v_pk_add_f32 v[4:5], v[10:11], v[8:9]
	s_nop 0
	v_sub_f32_e32 v9, v5, v9
	v_sub_f32_e32 v9, v11, v9
	v_add_f32_e32 v13, v12, v9
	v_mov_b32_e32 v12, v10
	v_pk_add_f32 v[10:11], v[4:5], v[10:11] neg_lo:[0,1] neg_hi:[0,1]
	v_pk_add_f32 v[14:15], v[4:5], v[12:13]
	v_mov_b32_e32 v9, v4
	v_mov_b32_e32 v11, v15
	v_pk_add_f32 v[16:17], v[8:9], v[10:11] neg_lo:[0,1] neg_hi:[0,1]
	v_pk_add_f32 v[8:9], v[8:9], v[10:11]
	v_mov_b32_e32 v12, v13
	v_pk_add_f32 v[10:11], v[8:9], v[4:5] op_sel:[1,0] op_sel_hi:[0,1] neg_lo:[0,1] neg_hi:[0,1]
	v_pk_add_f32 v[18:19], v[14:15], v[10:11] op_sel_hi:[1,0] neg_lo:[0,1] neg_hi:[0,1]
	v_mov_b32_e32 v14, v15
	v_mov_b32_e32 v15, v9
	v_pk_mov_b32 v[10:11], v[4:5], v[10:11] op_sel:[1,0]
	v_mov_b32_e32 v13, v4
	v_pk_add_f32 v[10:11], v[14:15], v[10:11] neg_lo:[0,1] neg_hi:[0,1]
	v_mov_b32_e32 v18, v16
	v_pk_add_f32 v[4:5], v[12:13], v[10:11] neg_lo:[0,1] neg_hi:[0,1]
	v_mov_b32_e32 v17, v9
	v_pk_add_f32 v[10:11], v[18:19], v[4:5]
	s_nop 0
	v_pk_add_f32 v[12:13], v[10:11], v[10:11] op_sel:[0,1] op_sel_hi:[1,0]
	s_nop 0
	v_pk_add_f32 v[8:9], v[8:9], v[12:13] op_sel:[1,0] op_sel_hi:[0,1]
	v_mov_b32_e32 v11, v8
	v_pk_add_f32 v[14:15], v[10:11], v[16:17] neg_lo:[0,1] neg_hi:[0,1]
	v_mov_b32_e32 v5, v12
	v_sub_f32_e32 v9, v10, v14
	v_pk_add_f32 v[4:5], v[4:5], v[14:15] neg_lo:[0,1] neg_hi:[0,1]
	v_sub_f32_e32 v9, v16, v9
	v_add_f32_e32 v4, v4, v9
	v_add_f32_e32 v4, v4, v5
	v_add_f32_e32 v4, v8, v4
	v_cndmask_b32_e32 v4, v153, v4, vcc
	v_cmp_ngt_f32_e32 vcc, -1.0, v1
	v_max_f32_e32 v14, v6, v6
	v_lshl_add_u64 v[10:11], s[6:7], 0, v[42:43]
	v_cndmask_b32_e32 v4, v154, v4, vcc
	v_cmp_neq_f32_e32 vcc, -1.0, v1
	v_lshl_add_u64 v[10:11], v[10:11], 0, v[2:3]
	s_nop 0
	v_cndmask_b32_e32 v4, v155, v4, vcc
	v_cmp_lt_f32_e64 vcc, |v1|, s49
	s_nop 1
	v_cndmask_b32_e32 v1, v4, v1, vcc
	v_sub_f32_e32 v1, v20, v1
	v_pk_add_f32 v[52:53], v[0:1], v[32:33]
	s_nop 0
	v_sub_f32_e32 v26, v52, v53
	v_max_f32_e32 v4, 0xff800000, v26
	v_max_f32_e32 v52, v14, v4
	v_sub_f32_e32 v1, v6, v52
	v_mul_f32_e32 v1, 0x3fb8aa3b, v1
	v_exp_f32_e32 v8, v1
	v_mov_b32_e32 v12, v186
	v_mov_b32_e32 v1, v187
	s_waitcnt vmcnt(0) lgkmcnt(0)
	v_add_f32_e32 v1, v7, v1
	v_min_f32_e32 v5, 0, v1
	v_mul_f32_e64 v1, |v1|, s45
	v_exp_f32_e32 v1, v1
	s_nop 0
	v_add_f32_e32 v9, 1.0, v1
	v_add_f32_e32 v10, -1.0, v9
	v_sub_f32_e32 v11, v10, v9
	v_add_f32_e32 v11, 1.0, v11
	v_sub_f32_e32 v10, v1, v10
	v_add_f32_e32 v13, v10, v11
	v_frexp_mant_f32_e32 v10, v9
	v_cmp_gt_f32_e32 vcc, s46, v10
	v_cvt_f64_f32_e32 v[10:11], v9
	v_frexp_exp_i32_f64_e32 v10, v[10:11]
	v_subbrev_co_u32_e32 v15, vcc, 0, v10, vcc
	v_sub_u32_e32 v10, 0, v15
	v_ldexp_f32 v9, v9, v10
	v_ldexp_f32 v10, v13, v10
	v_add_f32_e32 v13, -1.0, v9
	v_add_f32_e32 v11, 1.0, v13
	v_sub_f32_e32 v11, v9, v11
	v_add_f32_e32 v16, v10, v11
	v_add_f32_e32 v11, 1.0, v9
	v_add_f32_e32 v17, -1.0, v11
	v_sub_f32_e32 v9, v9, v17
	v_add_f32_e32 v9, v10, v9
	v_add_f32_e32 v22, v11, v9
	v_rcp_f32_e32 v23, v22
	v_sub_f32_e32 v10, v22, v11
	v_add_f32_e32 v11, v13, v16
	v_sub_f32_e32 v9, v9, v10
	v_sub_f32_e32 v10, v11, v13
	v_mul_f32_e32 v24, v11, v23
	v_sub_f32_e32 v13, v16, v10
	v_mul_f32_e32 v16, v22, v24
	v_fma_f32 v18, v24, v22, -v16
	v_fmac_f32_e32 v18, v24, v9
	v_add_f32_e32 v10, v16, v18
	v_sub_f32_e32 v17, v11, v10
	v_pk_add_f32 v[20:21], v[10:11], v[16:17] neg_lo:[0,1] neg_hi:[0,1]
	v_mov_b32_e32 v19, v10
	v_pk_add_f32 v[10:11], v[20:21], v[18:19] neg_lo:[0,1] neg_hi:[0,1]
	v_cmp_neq_f32_e32 vcc, s48, v1
	v_add_f32_e32 v11, v13, v11
	v_add_f32_e32 v10, v10, v11
	v_add_f32_e32 v11, v17, v10
	v_mul_f32_e32 v13, v23, v11
	v_mul_f32_e32 v16, v22, v13
	v_fma_f32 v18, v13, v22, -v16
	v_fmac_f32_e32 v18, v13, v9
	v_sub_f32_e32 v9, v17, v11
	v_add_f32_e32 v9, v10, v9
	v_add_f32_e32 v10, v16, v18
	v_sub_f32_e32 v17, v11, v10
	v_pk_add_f32 v[20:21], v[10:11], v[16:17] neg_lo:[0,1] neg_hi:[0,1]
	v_mov_b32_e32 v19, v10
	v_pk_add_f32 v[10:11], v[20:21], v[18:19] neg_lo:[0,1] neg_hi:[0,1]
	s_nop 0
	v_add_f32_e32 v9, v9, v11
	v_add_f32_e32 v9, v10, v9
	v_add_f32_e32 v11, v24, v13
	v_add_f32_e32 v9, v17, v9
	v_sub_f32_e32 v10, v11, v24
	v_mul_f32_e32 v9, v23, v9
	v_sub_f32_e32 v10, v13, v10
	v_add_f32_e32 v9, v10, v9
	v_add_f32_e32 v13, v11, v9
	v_mul_f32_e32 v16, v13, v13
	v_fmamk_f32 v10, v16, 0x3e9b6dac, v152
	v_fmaak_f32 v35, v16, v10, 0x3f2aaada
	v_cvt_f32_i32_e32 v10, v15
	v_sub_f32_e32 v11, v13, v11
	v_sub_f32_e32 v9, v9, v11
	v_mul_f32_e32 v11, v13, v16
	v_pk_mul_f32 v[18:19], v[10:11], v[34:35]
	v_ldexp_f32 v17, v13, 1
	v_fma_f32 v16, v10, s47, -v18
	v_fmac_f32_e32 v16, 0xb102e308, v10
	v_pk_add_f32 v[10:11], v[18:19], v[16:17]
	v_ldexp_f32 v9, v9, 1
	v_sub_f32_e32 v13, v11, v17
	v_sub_f32_e32 v13, v19, v13
	v_add_f32_e32 v21, v9, v13
	v_mov_b32_e32 v20, v18
	v_pk_add_f32 v[18:19], v[10:11], v[18:19] neg_lo:[0,1] neg_hi:[0,1]
	v_pk_add_f32 v[22:23], v[10:11], v[20:21]
	v_mov_b32_e32 v17, v10
	v_mov_b32_e32 v19, v23
	v_pk_add_f32 v[24:25], v[16:17], v[18:19] neg_lo:[0,1] neg_hi:[0,1]
	v_pk_add_f32 v[16:17], v[16:17], v[18:19]
	v_mov_b32_e32 v20, v21
	v_pk_add_f32 v[18:19], v[16:17], v[10:11] op_sel:[1,0] op_sel_hi:[0,1] neg_lo:[0,1] neg_hi:[0,1]
	v_pk_add_f32 v[28:29], v[22:23], v[18:19] op_sel_hi:[1,0] neg_lo:[0,1] neg_hi:[0,1]
	v_mov_b32_e32 v22, v23
	v_mov_b32_e32 v23, v17
	v_pk_mov_b32 v[18:19], v[10:11], v[18:19] op_sel:[1,0]
	v_mov_b32_e32 v21, v10
	v_pk_add_f32 v[18:19], v[22:23], v[18:19] neg_lo:[0,1] neg_hi:[0,1]
	v_mov_b32_e32 v28, v24
	v_pk_add_f32 v[10:11], v[20:21], v[18:19] neg_lo:[0,1] neg_hi:[0,1]
	v_mov_b32_e32 v25, v17
	v_pk_add_f32 v[18:19], v[28:29], v[10:11]
	s_nop 0
	v_pk_add_f32 v[20:21], v[18:19], v[18:19] op_sel:[0,1] op_sel_hi:[1,0]
	s_nop 0
	v_pk_add_f32 v[16:17], v[16:17], v[20:21] op_sel:[1,0] op_sel_hi:[0,1]
	v_mov_b32_e32 v19, v16
	v_pk_add_f32 v[22:23], v[18:19], v[24:25] neg_lo:[0,1] neg_hi:[0,1]
	v_mov_b32_e32 v11, v20
	v_sub_f32_e32 v9, v18, v22
	v_pk_add_f32 v[10:11], v[10:11], v[22:23] neg_lo:[0,1] neg_hi:[0,1]
	v_sub_f32_e32 v9, v24, v9
	v_add_f32_e32 v9, v10, v9
	v_add_f32_e32 v9, v9, v11
	v_add_f32_e32 v9, v16, v9
	v_cndmask_b32_e32 v9, v153, v9, vcc
	v_cmp_ngt_f32_e32 vcc, -1.0, v1
	v_lshl_add_u64 v[10:11], s[6:7], 0, v[46:47]
	v_lshl_add_u64 v[10:11], v[10:11], 0, v[2:3]
	v_cndmask_b32_e32 v9, v154, v9, vcc
	v_cmp_neq_f32_e32 vcc, -1.0, v1
	s_nop 1
	v_cndmask_b32_e32 v9, v155, v9, vcc
	v_cmp_lt_f32_e64 vcc, |v1|, s49
	s_nop 1
	v_cndmask_b32_e32 v1, v9, v1, vcc
	v_sub_f32_e32 v13, v5, v1
	v_mov_b32_e32 v1, v53
	v_pk_add_f32 v[50:51], v[0:1], v[12:13]
	s_nop 0
	v_sub_f32_e32 v27, v50, v51
	v_max_f32_e32 v4, v4, v27
	v_max_f32_e32 v50, v14, v4
	v_sub_f32_e32 v1, v6, v50
	v_mul_f32_e32 v1, 0x3fb8aa3b, v1
	v_exp_f32_e32 v9, v1
	v_mov_b32_e32 v12, v188
	v_mov_b32_e32 v1, v189
	s_waitcnt vmcnt(0) lgkmcnt(0)
	v_add_f32_e32 v1, v7, v1
	v_min_f32_e32 v5, 0, v1
	v_mul_f32_e64 v1, |v1|, s45
	v_exp_f32_e32 v1, v1
	s_nop 0
	v_add_f32_e32 v13, 1.0, v1
	v_add_f32_e32 v10, -1.0, v13
	v_sub_f32_e32 v11, v10, v13
	v_add_f32_e32 v11, 1.0, v11
	v_sub_f32_e32 v10, v1, v10
	v_add_f32_e32 v15, v10, v11
	v_frexp_mant_f32_e32 v10, v13
	v_cmp_gt_f32_e32 vcc, s46, v10
	v_cvt_f64_f32_e32 v[10:11], v13
	v_frexp_exp_i32_f64_e32 v10, v[10:11]
	v_subbrev_co_u32_e32 v22, vcc, 0, v10, vcc
	v_sub_u32_e32 v10, 0, v22
	v_ldexp_f32 v11, v13, v10
	v_add_f32_e32 v13, -1.0, v11
	v_add_f32_e32 v16, 1.0, v11
	v_ldexp_f32 v10, v15, v10
	v_add_f32_e32 v15, 1.0, v13
	v_add_f32_e32 v17, -1.0, v16
	v_sub_f32_e32 v15, v11, v15
	v_sub_f32_e32 v11, v11, v17
	v_add_f32_e32 v15, v10, v15
	v_add_f32_e32 v10, v10, v11
	v_add_f32_e32 v23, v16, v10
	v_rcp_f32_e32 v25, v23
	v_sub_f32_e32 v11, v23, v16
	v_sub_f32_e32 v24, v10, v11
	v_add_f32_e32 v11, v13, v15
	v_sub_f32_e32 v10, v11, v13
	v_sub_f32_e32 v13, v15, v10
	v_mul_f32_e32 v15, v11, v25
	v_mul_f32_e32 v16, v23, v15
	v_fma_f32 v18, v15, v23, -v16
	v_fmac_f32_e32 v18, v15, v24
	v_add_f32_e32 v10, v16, v18
	v_sub_f32_e32 v17, v11, v10
	v_pk_add_f32 v[20:21], v[10:11], v[16:17] neg_lo:[0,1] neg_hi:[0,1]
	v_mov_b32_e32 v19, v10
	v_pk_add_f32 v[10:11], v[20:21], v[18:19] neg_lo:[0,1] neg_hi:[0,1]
	v_cmp_neq_f32_e32 vcc, s48, v1
	v_add_f32_e32 v11, v13, v11
	v_add_f32_e32 v10, v10, v11
	v_add_f32_e32 v11, v17, v10
	v_mul_f32_e32 v13, v25, v11
	v_mul_f32_e32 v16, v23, v13
	v_fma_f32 v18, v13, v23, -v16
	v_fmac_f32_e32 v18, v13, v24
	v_sub_f32_e32 v17, v17, v11
	v_add_f32_e32 v23, v10, v17
	v_add_f32_e32 v10, v16, v18
	v_sub_f32_e32 v17, v11, v10
	v_pk_add_f32 v[20:21], v[10:11], v[16:17] neg_lo:[0,1] neg_hi:[0,1]
	v_mov_b32_e32 v19, v10
	v_pk_add_f32 v[10:11], v[20:21], v[18:19] neg_lo:[0,1] neg_hi:[0,1]
	s_nop 0
	v_add_f32_e32 v11, v23, v11
	v_add_f32_e32 v10, v10, v11
	v_add_f32_e32 v11, v15, v13
	v_add_f32_e32 v10, v17, v10
	v_sub_f32_e32 v15, v11, v15
	v_mul_f32_e32 v10, v25, v10
	v_sub_f32_e32 v13, v13, v15
	v_add_f32_e32 v13, v13, v10
	v_add_f32_e32 v15, v11, v13
	v_mul_f32_e32 v16, v15, v15
	v_fmamk_f32 v10, v16, 0x3e9b6dac, v152
	v_fmaak_f32 v35, v16, v10, 0x3f2aaada
	v_cvt_f32_i32_e32 v10, v22
	v_sub_f32_e32 v11, v15, v11
	v_sub_f32_e32 v11, v13, v11
	v_ldexp_f32 v13, v11, 1
	v_mul_f32_e32 v11, v15, v16
	v_pk_mul_f32 v[18:19], v[10:11], v[34:35]
	v_ldexp_f32 v17, v15, 1
	v_fma_f32 v16, v10, s47, -v18
	v_fmac_f32_e32 v16, 0xb102e308, v10
	v_pk_add_f32 v[10:11], v[18:19], v[16:17]
	v_mov_b32_e32 v20, v18
	v_sub_f32_e32 v15, v11, v17
	v_sub_f32_e32 v15, v19, v15
	v_add_f32_e32 v21, v13, v15
	v_pk_add_f32 v[18:19], v[10:11], v[18:19] neg_lo:[0,1] neg_hi:[0,1]
	v_pk_add_f32 v[22:23], v[10:11], v[20:21]
	v_mov_b32_e32 v17, v10
	v_mov_b32_e32 v19, v23
	v_pk_add_f32 v[24:25], v[16:17], v[18:19] neg_lo:[0,1] neg_hi:[0,1]
	v_pk_add_f32 v[16:17], v[16:17], v[18:19]
	v_mov_b32_e32 v20, v21
	v_pk_add_f32 v[18:19], v[16:17], v[10:11] op_sel:[1,0] op_sel_hi:[0,1] neg_lo:[0,1] neg_hi:[0,1]
	v_pk_add_f32 v[28:29], v[22:23], v[18:19] op_sel_hi:[1,0] neg_lo:[0,1] neg_hi:[0,1]
	v_mov_b32_e32 v22, v23
	v_mov_b32_e32 v23, v17
	v_pk_mov_b32 v[18:19], v[10:11], v[18:19] op_sel:[1,0]
	v_mov_b32_e32 v21, v10
	v_pk_add_f32 v[18:19], v[22:23], v[18:19] neg_lo:[0,1] neg_hi:[0,1]
	v_mov_b32_e32 v28, v24
	v_pk_add_f32 v[10:11], v[20:21], v[18:19] neg_lo:[0,1] neg_hi:[0,1]
	v_mov_b32_e32 v25, v17
	v_pk_add_f32 v[18:19], v[28:29], v[10:11]
	s_nop 0
	v_pk_add_f32 v[20:21], v[18:19], v[18:19] op_sel:[0,1] op_sel_hi:[1,0]
	s_nop 0
	v_pk_add_f32 v[16:17], v[16:17], v[20:21] op_sel:[1,0] op_sel_hi:[0,1]
	v_mov_b32_e32 v19, v16
	v_pk_add_f32 v[22:23], v[18:19], v[24:25] neg_lo:[0,1] neg_hi:[0,1]
	v_mov_b32_e32 v11, v20
	v_sub_f32_e32 v13, v18, v22
	v_pk_add_f32 v[10:11], v[10:11], v[22:23] neg_lo:[0,1] neg_hi:[0,1]
	v_sub_f32_e32 v13, v24, v13
	v_add_f32_e32 v10, v10, v13
	v_add_f32_e32 v10, v10, v11
	v_add_f32_e32 v10, v16, v10
	v_cndmask_b32_e32 v10, v153, v10, vcc
	v_cmp_ngt_f32_e32 vcc, -1.0, v1
	s_nop 1
	v_cndmask_b32_e32 v10, v154, v10, vcc
	v_cmp_neq_f32_e32 vcc, -1.0, v1
	s_nop 1
	v_cndmask_b32_e32 v10, v155, v10, vcc
	v_cmp_lt_f32_e64 vcc, |v1|, s49
	s_nop 1
	v_cndmask_b32_e32 v1, v10, v1, vcc
	v_sub_f32_e32 v13, v5, v1
	v_mov_b32_e32 v1, v51
	v_pk_add_f32 v[58:59], v[0:1], v[12:13]
	s_nop 0
	v_sub_f32_e32 v28, v58, v59
	v_max_f32_e32 v11, v4, v28
	v_max_f32_e32 v58, v14, v11
	v_sub_f32_e32 v1, v6, v58
	v_lshl_add_u64 v[4:5], s[6:7], 0, v[54:55]
	v_mul_f32_e32 v1, 0x3fb8aa3b, v1
	v_lshl_add_u64 v[12:13], v[4:5], 0, v[2:3]
	v_exp_f32_e32 v10, v1
	v_mov_b32_e32 v4, v190
	v_mov_b32_e32 v1, v191
	s_waitcnt vmcnt(0) lgkmcnt(0)
	v_add_f32_e32 v1, v7, v1
	v_min_f32_e32 v5, 0, v1
	v_mul_f32_e64 v1, |v1|, s45
	v_exp_f32_e32 v1, v1
	s_nop 0
	v_add_f32_e32 v15, 1.0, v1
	v_add_f32_e32 v12, -1.0, v15
	v_sub_f32_e32 v13, v12, v15
	v_add_f32_e32 v13, 1.0, v13
	v_sub_f32_e32 v12, v1, v12
	v_add_f32_e32 v16, v12, v13
	v_frexp_mant_f32_e32 v12, v15
	v_cmp_gt_f32_e32 vcc, s46, v12
	v_cvt_f64_f32_e32 v[12:13], v15
	v_frexp_exp_i32_f64_e32 v12, v[12:13]
	v_subbrev_co_u32_e32 v22, vcc, 0, v12, vcc
	v_sub_u32_e32 v12, 0, v22
	v_ldexp_f32 v13, v15, v12
	v_add_f32_e32 v15, -1.0, v13
	v_add_f32_e32 v17, 1.0, v13
	v_ldexp_f32 v12, v16, v12
	v_add_f32_e32 v16, 1.0, v15
	v_add_f32_e32 v18, -1.0, v17
	v_sub_f32_e32 v16, v13, v16
	v_sub_f32_e32 v13, v13, v18
	v_add_f32_e32 v16, v12, v16
	v_add_f32_e32 v12, v12, v13
	v_add_f32_e32 v23, v17, v12
	v_rcp_f32_e32 v25, v23
	v_sub_f32_e32 v13, v23, v17
	v_sub_f32_e32 v24, v12, v13
	v_add_f32_e32 v13, v15, v16
	v_sub_f32_e32 v12, v13, v15
	v_mul_f32_e32 v29, v13, v25
	v_sub_f32_e32 v15, v16, v12
	v_mul_f32_e32 v16, v23, v29
	v_fma_f32 v18, v29, v23, -v16
	v_fmac_f32_e32 v18, v29, v24
	v_add_f32_e32 v12, v16, v18
	v_sub_f32_e32 v17, v13, v12
	v_pk_add_f32 v[20:21], v[12:13], v[16:17] neg_lo:[0,1] neg_hi:[0,1]
	v_mov_b32_e32 v19, v12
	v_pk_add_f32 v[12:13], v[20:21], v[18:19] neg_lo:[0,1] neg_hi:[0,1]
	v_cmp_neq_f32_e32 vcc, s48, v1
	v_add_f32_e32 v13, v15, v13
	v_add_f32_e32 v12, v12, v13
	v_add_f32_e32 v13, v17, v12
	v_mul_f32_e32 v15, v25, v13
	v_mul_f32_e32 v16, v23, v15
	v_fma_f32 v18, v15, v23, -v16
	v_fmac_f32_e32 v18, v15, v24
	v_sub_f32_e32 v17, v17, v13
	v_add_f32_e32 v23, v12, v17
	v_add_f32_e32 v12, v16, v18
	v_sub_f32_e32 v17, v13, v12
	v_pk_add_f32 v[20:21], v[12:13], v[16:17] neg_lo:[0,1] neg_hi:[0,1]
	v_mov_b32_e32 v19, v12
	v_pk_add_f32 v[12:13], v[20:21], v[18:19] neg_lo:[0,1] neg_hi:[0,1]
	s_nop 0
	v_add_f32_e32 v13, v23, v13
	v_add_f32_e32 v12, v12, v13
	v_add_f32_e32 v13, v29, v15
	v_add_f32_e32 v12, v17, v12
	v_sub_f32_e32 v16, v13, v29
	v_mul_f32_e32 v12, v25, v12
	v_sub_f32_e32 v15, v15, v16
	v_add_f32_e32 v15, v15, v12
	v_add_f32_e32 v16, v13, v15
	v_mul_f32_e32 v18, v16, v16
	v_fmamk_f32 v12, v18, 0x3e9b6dac, v152
	v_fmaak_f32 v35, v18, v12, 0x3f2aaada
	v_cvt_f32_i32_e32 v12, v22
	v_sub_f32_e32 v13, v16, v13
	v_sub_f32_e32 v13, v15, v13
	v_ldexp_f32 v15, v13, 1
	v_mul_f32_e32 v13, v16, v18
	v_pk_mul_f32 v[18:19], v[12:13], v[34:35]
	v_ldexp_f32 v17, v16, 1
	v_fma_f32 v16, v12, s47, -v18
	v_fmac_f32_e32 v16, 0xb102e308, v12
	v_pk_add_f32 v[12:13], v[18:19], v[16:17]
	v_mov_b32_e32 v20, v18
	v_sub_f32_e32 v17, v13, v17
	v_sub_f32_e32 v17, v19, v17
	v_add_f32_e32 v21, v15, v17
	v_pk_add_f32 v[18:19], v[12:13], v[18:19] neg_lo:[0,1] neg_hi:[0,1]
	v_pk_add_f32 v[22:23], v[12:13], v[20:21]
	v_mov_b32_e32 v17, v12
	v_mov_b32_e32 v19, v23
	v_pk_add_f32 v[24:25], v[16:17], v[18:19] neg_lo:[0,1] neg_hi:[0,1]
	v_pk_add_f32 v[16:17], v[16:17], v[18:19]
	v_mov_b32_e32 v20, v21
	v_pk_add_f32 v[18:19], v[16:17], v[12:13] op_sel:[1,0] op_sel_hi:[0,1] neg_lo:[0,1] neg_hi:[0,1]
	v_pk_add_f32 v[30:31], v[22:23], v[18:19] op_sel_hi:[1,0] neg_lo:[0,1] neg_hi:[0,1]
	v_mov_b32_e32 v22, v23
	v_mov_b32_e32 v23, v17
	v_pk_mov_b32 v[18:19], v[12:13], v[18:19] op_sel:[1,0]
	v_mov_b32_e32 v21, v12
	v_pk_add_f32 v[18:19], v[22:23], v[18:19] neg_lo:[0,1] neg_hi:[0,1]
	v_mov_b32_e32 v30, v24
	v_pk_add_f32 v[12:13], v[20:21], v[18:19] neg_lo:[0,1] neg_hi:[0,1]
	v_mov_b32_e32 v25, v17
	v_pk_add_f32 v[18:19], v[30:31], v[12:13]
	s_nop 0
	v_pk_add_f32 v[20:21], v[18:19], v[18:19] op_sel:[0,1] op_sel_hi:[1,0]
	s_nop 0
	v_pk_add_f32 v[16:17], v[16:17], v[20:21] op_sel:[1,0] op_sel_hi:[0,1]
	v_mov_b32_e32 v19, v16
	v_pk_add_f32 v[22:23], v[18:19], v[24:25] neg_lo:[0,1] neg_hi:[0,1]
	v_mov_b32_e32 v13, v20
	v_sub_f32_e32 v15, v18, v22
	v_pk_add_f32 v[12:13], v[12:13], v[22:23] neg_lo:[0,1] neg_hi:[0,1]
	v_sub_f32_e32 v15, v24, v15
	v_add_f32_e32 v12, v12, v15
	v_add_f32_e32 v12, v12, v13
	v_add_f32_e32 v12, v16, v12
	v_cndmask_b32_e32 v12, v153, v12, vcc
	v_cmp_ngt_f32_e32 vcc, -1.0, v1
	s_nop 1
	v_cndmask_b32_e32 v12, v154, v12, vcc
	v_cmp_neq_f32_e32 vcc, -1.0, v1
	s_nop 1
	v_cndmask_b32_e32 v12, v155, v12, vcc
	v_cmp_lt_f32_e64 vcc, |v1|, s49
	s_nop 1
	v_cndmask_b32_e32 v1, v12, v1, vcc
	v_sub_f32_e32 v5, v5, v1
	v_mov_b32_e32 v1, v59
	v_pk_add_f32 v[66:67], v[0:1], v[4:5]
	v_lshl_add_u64 v[4:5], s[6:7], 0, v[60:61]
	v_sub_f32_e32 v29, v66, v67
	v_max_f32_e32 v15, v11, v29
	v_max_f32_e32 v66, v14, v15
	v_sub_f32_e32 v1, v6, v66
	v_mul_f32_e32 v1, 0x3fb8aa3b, v1
	v_lshl_add_u64 v[4:5], v[4:5], 0, v[2:3]
	v_exp_f32_e32 v11, v1
	v_mov_b32_e32 v12, v192
	v_mov_b32_e32 v1, v193
	s_waitcnt vmcnt(0) lgkmcnt(0)
	v_add_f32_e32 v1, v7, v1
	v_min_f32_e32 v13, 0, v1
	v_mul_f32_e64 v1, |v1|, s45
	v_exp_f32_e32 v1, v1
	s_nop 0
	v_add_f32_e32 v16, 1.0, v1
	v_add_f32_e32 v4, -1.0, v16
	v_sub_f32_e32 v5, v4, v16
	v_add_f32_e32 v5, 1.0, v5
	v_sub_f32_e32 v4, v1, v4
	v_add_f32_e32 v17, v4, v5
	v_frexp_mant_f32_e32 v4, v16
	v_cmp_gt_f32_e32 vcc, s46, v4
	v_cvt_f64_f32_e32 v[4:5], v16
	v_frexp_exp_i32_f64_e32 v4, v[4:5]
	v_subbrev_co_u32_e32 v22, vcc, 0, v4, vcc
	v_sub_u32_e32 v4, 0, v22
	v_ldexp_f32 v5, v16, v4
	v_add_f32_e32 v16, -1.0, v5
	v_add_f32_e32 v18, 1.0, v5
	v_ldexp_f32 v4, v17, v4
	v_add_f32_e32 v17, 1.0, v16
	v_add_f32_e32 v19, -1.0, v18
	v_sub_f32_e32 v17, v5, v17
	v_sub_f32_e32 v5, v5, v19
	v_add_f32_e32 v17, v4, v17
	v_add_f32_e32 v4, v4, v5
	v_add_f32_e32 v23, v18, v4
	v_rcp_f32_e32 v25, v23
	v_sub_f32_e32 v5, v23, v18
	v_sub_f32_e32 v24, v4, v5
	v_add_f32_e32 v5, v16, v17
	v_mul_f32_e32 v31, v5, v25
	v_sub_f32_e32 v4, v5, v16
	v_mul_f32_e32 v16, v23, v31
	v_fma_f32 v18, v31, v23, -v16
	v_fmac_f32_e32 v18, v31, v24
	v_sub_f32_e32 v30, v17, v4
	v_add_f32_e32 v4, v16, v18
	v_sub_f32_e32 v17, v5, v4
	v_pk_add_f32 v[20:21], v[4:5], v[16:17] neg_lo:[0,1] neg_hi:[0,1]
	v_mov_b32_e32 v19, v4
	v_pk_add_f32 v[4:5], v[20:21], v[18:19] neg_lo:[0,1] neg_hi:[0,1]
	v_cmp_neq_f32_e32 vcc, s48, v1
	v_add_f32_e32 v5, v30, v5
	v_add_f32_e32 v4, v4, v5
	v_add_f32_e32 v5, v17, v4
	v_mul_f32_e32 v30, v25, v5
	v_mul_f32_e32 v16, v23, v30
	v_fma_f32 v18, v30, v23, -v16
	v_fmac_f32_e32 v18, v30, v24
	v_sub_f32_e32 v17, v17, v5
	v_add_f32_e32 v23, v4, v17
	v_add_f32_e32 v4, v16, v18
	v_sub_f32_e32 v17, v5, v4
	v_pk_add_f32 v[20:21], v[4:5], v[16:17] neg_lo:[0,1] neg_hi:[0,1]
	v_mov_b32_e32 v19, v4
	v_pk_add_f32 v[4:5], v[20:21], v[18:19] neg_lo:[0,1] neg_hi:[0,1]
	s_nop 0
	v_add_f32_e32 v5, v23, v5
	v_add_f32_e32 v4, v4, v5
	v_add_f32_e32 v5, v31, v30
	v_add_f32_e32 v4, v17, v4
	v_sub_f32_e32 v16, v5, v31
	v_mul_f32_e32 v4, v25, v4
	v_sub_f32_e32 v16, v30, v16
	v_add_f32_e32 v16, v16, v4
	v_add_f32_e32 v18, v5, v16
	v_mul_f32_e32 v19, v18, v18
	v_fmamk_f32 v4, v19, 0x3e9b6dac, v152
	v_fmaak_f32 v35, v19, v4, 0x3f2aaada
	v_cvt_f32_i32_e32 v4, v22
	v_sub_f32_e32 v5, v18, v5
	v_sub_f32_e32 v5, v16, v5
	v_ldexp_f32 v20, v5, 1
	v_mul_f32_e32 v5, v18, v19
	v_ldexp_f32 v17, v18, 1
	v_pk_mul_f32 v[18:19], v[4:5], v[34:35]
	s_nop 0
	v_fma_f32 v16, v4, s47, -v18
	v_fmac_f32_e32 v16, 0xb102e308, v4
	v_pk_add_f32 v[4:5], v[18:19], v[16:17]
	s_nop 0
	v_sub_f32_e32 v17, v5, v17
	v_sub_f32_e32 v17, v19, v17
	v_add_f32_e32 v21, v20, v17
	v_mov_b32_e32 v20, v18
	v_pk_add_f32 v[18:19], v[4:5], v[18:19] neg_lo:[0,1] neg_hi:[0,1]
	v_pk_add_f32 v[22:23], v[4:5], v[20:21]
	v_mov_b32_e32 v17, v4
	v_mov_b32_e32 v19, v23
	v_pk_add_f32 v[24:25], v[16:17], v[18:19] neg_lo:[0,1] neg_hi:[0,1]
	v_pk_add_f32 v[16:17], v[16:17], v[18:19]
	v_mov_b32_e32 v20, v21
	v_pk_add_f32 v[18:19], v[16:17], v[4:5] op_sel:[1,0] op_sel_hi:[0,1] neg_lo:[0,1] neg_hi:[0,1]
	v_pk_add_f32 v[30:31], v[22:23], v[18:19] op_sel_hi:[1,0] neg_lo:[0,1] neg_hi:[0,1]
	v_mov_b32_e32 v22, v23
	v_mov_b32_e32 v23, v17
	v_pk_mov_b32 v[18:19], v[4:5], v[18:19] op_sel:[1,0]
	v_mov_b32_e32 v21, v4
	v_pk_add_f32 v[18:19], v[22:23], v[18:19] neg_lo:[0,1] neg_hi:[0,1]
	v_mov_b32_e32 v30, v24
	v_pk_add_f32 v[4:5], v[20:21], v[18:19] neg_lo:[0,1] neg_hi:[0,1]
	v_mov_b32_e32 v25, v17
	v_pk_add_f32 v[18:19], v[30:31], v[4:5]
	s_nop 0
	v_pk_add_f32 v[20:21], v[18:19], v[18:19] op_sel:[0,1] op_sel_hi:[1,0]
	s_nop 0
	v_pk_add_f32 v[16:17], v[16:17], v[20:21] op_sel:[1,0] op_sel_hi:[0,1]
	v_mov_b32_e32 v19, v16
	v_pk_add_f32 v[22:23], v[18:19], v[24:25] neg_lo:[0,1] neg_hi:[0,1]
	v_mov_b32_e32 v5, v20
	v_sub_f32_e32 v17, v18, v22
	v_pk_add_f32 v[4:5], v[4:5], v[22:23] neg_lo:[0,1] neg_hi:[0,1]
	v_sub_f32_e32 v17, v24, v17
	v_add_f32_e32 v4, v4, v17
	v_add_f32_e32 v4, v4, v5
	v_add_f32_e32 v4, v16, v4
	v_cndmask_b32_e32 v4, v153, v4, vcc
	v_cmp_ngt_f32_e32 vcc, -1.0, v1
	v_lshl_add_u64 v[16:17], s[6:7], 0, v[64:65]
	v_lshl_add_u64 v[16:17], v[16:17], 0, v[2:3]
	v_cndmask_b32_e32 v4, v154, v4, vcc
	v_cmp_neq_f32_e32 vcc, -1.0, v1
	s_nop 1
	v_cndmask_b32_e32 v4, v155, v4, vcc
	v_cmp_lt_f32_e64 vcc, |v1|, s49
	s_nop 1
	v_cndmask_b32_e32 v1, v4, v1, vcc
	v_sub_f32_e32 v13, v13, v1
	v_mov_b32_e32 v1, v67
	v_pk_add_f32 v[68:69], v[0:1], v[12:13]
	s_nop 0
	v_sub_f32_e32 v30, v68, v69
	v_max_f32_e32 v4, v15, v30
	v_max_f32_e32 v68, v14, v4
	v_sub_f32_e32 v1, v6, v68
	v_mul_f32_e32 v1, 0x3fb8aa3b, v1
	v_exp_f32_e32 v12, v1
	v_mov_b32_e32 v18, v194
	v_mov_b32_e32 v1, v195
	s_waitcnt vmcnt(0) lgkmcnt(0)
	v_add_f32_e32 v1, v7, v1
	v_min_f32_e32 v5, 0, v1
	v_mul_f32_e64 v1, |v1|, s45
	v_exp_f32_e32 v1, v1
	s_nop 0
	v_add_f32_e32 v13, 1.0, v1
	v_add_f32_e32 v15, -1.0, v13
	v_sub_f32_e32 v16, v15, v13
	v_add_f32_e32 v16, 1.0, v16
	v_sub_f32_e32 v15, v1, v15
	v_add_f32_e32 v15, v15, v16
	v_frexp_mant_f32_e32 v16, v13
	v_cmp_gt_f32_e32 vcc, s46, v16
	v_cvt_f64_f32_e32 v[16:17], v13
	v_frexp_exp_i32_f64_e32 v16, v[16:17]
	v_subbrev_co_u32_e32 v19, vcc, 0, v16, vcc
	v_sub_u32_e32 v16, 0, v19
	v_ldexp_f32 v13, v13, v16
	v_ldexp_f32 v15, v15, v16
	v_add_f32_e32 v16, -1.0, v13
	v_add_f32_e32 v17, 1.0, v16
	v_sub_f32_e32 v17, v13, v17
	v_add_f32_e32 v20, v15, v17
	v_add_f32_e32 v17, 1.0, v13
	v_add_f32_e32 v21, -1.0, v17
	v_sub_f32_e32 v13, v13, v21
	v_add_f32_e32 v13, v15, v13
	v_add_f32_e32 v15, v17, v13
	v_rcp_f32_e32 v31, v15
	v_sub_f32_e32 v17, v15, v17
	v_sub_f32_e32 v13, v13, v17
	v_add_f32_e32 v17, v16, v20
	v_sub_f32_e32 v16, v17, v16
	v_mul_f32_e32 v35, v17, v31
	v_sub_f32_e32 v32, v20, v16
	v_mul_f32_e32 v20, v15, v35
	v_fma_f32 v22, v35, v15, -v20
	v_fmac_f32_e32 v22, v35, v13
	v_add_f32_e32 v16, v20, v22
	v_sub_f32_e32 v21, v17, v16
	v_pk_add_f32 v[24:25], v[16:17], v[20:21] neg_lo:[0,1] neg_hi:[0,1]
	v_mov_b32_e32 v23, v16
	v_pk_add_f32 v[16:17], v[24:25], v[22:23] neg_lo:[0,1] neg_hi:[0,1]
	v_cmp_neq_f32_e32 vcc, s48, v1
	v_add_f32_e32 v17, v32, v17
	v_add_f32_e32 v16, v16, v17
	v_add_f32_e32 v17, v21, v16
	v_mul_f32_e32 v32, v31, v17
	v_mul_f32_e32 v20, v15, v32
	v_fma_f32 v22, v32, v15, -v20
	v_fmac_f32_e32 v22, v32, v13
	v_sub_f32_e32 v13, v21, v17
	v_add_f32_e32 v13, v16, v13
	v_add_f32_e32 v16, v20, v22
	v_sub_f32_e32 v21, v17, v16
	v_pk_add_f32 v[24:25], v[16:17], v[20:21] neg_lo:[0,1] neg_hi:[0,1]
	v_mov_b32_e32 v23, v16
	v_pk_add_f32 v[16:17], v[24:25], v[22:23] neg_lo:[0,1] neg_hi:[0,1]
	v_add_f32_e32 v15, v35, v32
	v_add_f32_e32 v13, v13, v17
	v_add_f32_e32 v13, v16, v13
	v_add_f32_e32 v13, v21, v13
	v_sub_f32_e32 v16, v15, v35
	v_mul_f32_e32 v13, v31, v13
	v_sub_f32_e32 v16, v32, v16
	v_add_f32_e32 v13, v16, v13
	v_add_f32_e32 v17, v15, v13
	v_mul_f32_e32 v20, v17, v17
	v_fmamk_f32 v16, v20, 0x3e9b6dac, v152
	v_fmaak_f32 v35, v20, v16, 0x3f2aaada
	v_cvt_f32_i32_e32 v16, v19
	v_sub_f32_e32 v15, v17, v15
	v_ldexp_f32 v21, v17, 1
	v_mul_f32_e32 v17, v17, v20
	v_pk_mul_f32 v[22:23], v[16:17], v[34:35]
	v_sub_f32_e32 v13, v13, v15
	v_fma_f32 v20, v16, s47, -v22
	v_fmac_f32_e32 v20, 0xb102e308, v16
	v_pk_add_f32 v[16:17], v[22:23], v[20:21]
	v_ldexp_f32 v13, v13, 1
	v_sub_f32_e32 v15, v17, v21
	v_sub_f32_e32 v15, v23, v15
	v_add_f32_e32 v25, v13, v15
	v_mov_b32_e32 v24, v22
	v_pk_add_f32 v[22:23], v[16:17], v[22:23] neg_lo:[0,1] neg_hi:[0,1]
	v_pk_add_f32 v[72:73], v[16:17], v[24:25]
	v_mov_b32_e32 v21, v16
	v_mov_b32_e32 v23, v73
	v_pk_add_f32 v[74:75], v[20:21], v[22:23] neg_lo:[0,1] neg_hi:[0,1]
	v_pk_add_f32 v[20:21], v[20:21], v[22:23]
	v_mov_b32_e32 v24, v25
	v_pk_add_f32 v[22:23], v[20:21], v[16:17] op_sel:[1,0] op_sel_hi:[0,1] neg_lo:[0,1] neg_hi:[0,1]
	v_pk_add_f32 v[76:77], v[72:73], v[22:23] op_sel_hi:[1,0] neg_lo:[0,1] neg_hi:[0,1]
	v_mov_b32_e32 v72, v73
	v_mov_b32_e32 v73, v21
	v_pk_mov_b32 v[22:23], v[16:17], v[22:23] op_sel:[1,0]
	v_mov_b32_e32 v25, v16
	v_pk_add_f32 v[22:23], v[72:73], v[22:23] neg_lo:[0,1] neg_hi:[0,1]
	v_mov_b32_e32 v76, v74
	v_pk_add_f32 v[16:17], v[24:25], v[22:23] neg_lo:[0,1] neg_hi:[0,1]
	v_mov_b32_e32 v75, v21
	v_pk_add_f32 v[22:23], v[76:77], v[16:17]
	s_nop 0
	v_pk_add_f32 v[24:25], v[22:23], v[22:23] op_sel:[0,1] op_sel_hi:[1,0]
	s_nop 0
	v_pk_add_f32 v[20:21], v[20:21], v[24:25] op_sel:[1,0] op_sel_hi:[0,1]
	v_mov_b32_e32 v23, v20
	v_pk_add_f32 v[72:73], v[22:23], v[74:75] neg_lo:[0,1] neg_hi:[0,1]
	v_mov_b32_e32 v17, v24
	v_sub_f32_e32 v13, v22, v72
	v_pk_add_f32 v[16:17], v[16:17], v[72:73] neg_lo:[0,1] neg_hi:[0,1]
	v_sub_f32_e32 v13, v74, v13
	v_add_f32_e32 v13, v16, v13
	v_add_f32_e32 v13, v13, v17
	v_add_f32_e32 v13, v20, v13
	v_cndmask_b32_e32 v13, v153, v13, vcc
	v_cmp_ngt_f32_e32 vcc, -1.0, v1
	v_add_u32_e32 v74, 6, v40
	v_ashrrev_i32_e32 v75, 31, v74
	v_cndmask_b32_e32 v13, v154, v13, vcc
	v_cmp_neq_f32_e32 vcc, -1.0, v1
	v_lshlrev_b64 v[72:73], 5, v[74:75]
	v_lshl_add_u64 v[16:17], s[6:7], 0, v[72:73]
	v_cndmask_b32_e32 v13, v155, v13, vcc
	v_cmp_lt_f32_e64 vcc, |v1|, s49
	v_lshl_add_u64 v[16:17], v[16:17], 0, v[2:3]
	s_nop 0
	v_cndmask_b32_e32 v1, v13, v1, vcc
	v_sub_f32_e32 v19, v5, v1
	v_mov_b32_e32 v1, v69
	v_pk_add_f32 v[76:77], v[0:1], v[18:19]
	s_nop 0
	v_sub_f32_e32 v31, v76, v77
	v_max_f32_e32 v4, v4, v31
	v_max_f32_e32 v76, v14, v4
	v_sub_f32_e32 v1, v6, v76
	v_mul_f32_e32 v1, 0x3fb8aa3b, v1
	v_exp_f32_e32 v13, v1
	v_mov_b32_e32 v18, v196
	v_mov_b32_e32 v1, v197
	s_waitcnt vmcnt(0) lgkmcnt(0)
	v_add_f32_e32 v1, v7, v1
	v_min_f32_e32 v5, 0, v1
	v_mul_f32_e64 v1, |v1|, s45
	v_exp_f32_e32 v1, v1
	s_nop 0
	v_add_f32_e32 v15, 1.0, v1
	v_add_f32_e32 v16, -1.0, v15
	v_sub_f32_e32 v17, v16, v15
	v_add_f32_e32 v17, 1.0, v17
	v_sub_f32_e32 v16, v1, v16
	v_add_f32_e32 v19, v16, v17
	v_frexp_mant_f32_e32 v16, v15
	v_cmp_gt_f32_e32 vcc, s46, v16
	v_cvt_f64_f32_e32 v[16:17], v15
	v_frexp_exp_i32_f64_e32 v16, v[16:17]
	v_subbrev_co_u32_e32 v32, vcc, 0, v16, vcc
	v_sub_u32_e32 v16, 0, v32
	v_ldexp_f32 v15, v15, v16
	v_ldexp_f32 v16, v19, v16
	v_add_f32_e32 v19, -1.0, v15
	v_add_f32_e32 v17, 1.0, v19
	v_sub_f32_e32 v17, v15, v17
	v_add_f32_e32 v20, v16, v17
	v_add_f32_e32 v17, 1.0, v15
	v_add_f32_e32 v21, -1.0, v17
	v_sub_f32_e32 v15, v15, v21
	v_add_f32_e32 v15, v16, v15
	v_add_f32_e32 v35, v17, v15
	v_rcp_f32_e32 v37, v35
	v_sub_f32_e32 v16, v35, v17
	v_add_f32_e32 v17, v19, v20
	v_sub_f32_e32 v15, v15, v16
	v_sub_f32_e32 v16, v17, v19
	v_mul_f32_e32 v78, v17, v37
	v_sub_f32_e32 v19, v20, v16
	v_mul_f32_e32 v20, v35, v78
	v_fma_f32 v22, v78, v35, -v20
	v_fmac_f32_e32 v22, v78, v15
	v_add_f32_e32 v16, v20, v22
	v_sub_f32_e32 v21, v17, v16
	v_pk_add_f32 v[24:25], v[16:17], v[20:21] neg_lo:[0,1] neg_hi:[0,1]
	v_mov_b32_e32 v23, v16
	v_pk_add_f32 v[16:17], v[24:25], v[22:23] neg_lo:[0,1] neg_hi:[0,1]
	v_cmp_neq_f32_e32 vcc, s48, v1
	v_add_f32_e32 v17, v19, v17
	v_add_f32_e32 v16, v16, v17
	v_add_f32_e32 v17, v21, v16
	v_mul_f32_e32 v19, v37, v17
	v_mul_f32_e32 v20, v35, v19
	v_fma_f32 v22, v19, v35, -v20
	v_fmac_f32_e32 v22, v19, v15
	v_sub_f32_e32 v15, v21, v17
	v_add_f32_e32 v15, v16, v15
	v_add_f32_e32 v16, v20, v22
	v_sub_f32_e32 v21, v17, v16
	v_pk_add_f32 v[24:25], v[16:17], v[20:21] neg_lo:[0,1] neg_hi:[0,1]
	v_mov_b32_e32 v23, v16
	v_pk_add_f32 v[16:17], v[24:25], v[22:23] neg_lo:[0,1] neg_hi:[0,1]
	s_nop 0
	v_add_f32_e32 v15, v15, v17
	v_add_f32_e32 v15, v16, v15
	v_add_f32_e32 v17, v78, v19
	v_add_f32_e32 v15, v21, v15
	v_sub_f32_e32 v16, v17, v78
	v_mul_f32_e32 v15, v37, v15
	v_sub_f32_e32 v16, v19, v16
	v_add_f32_e32 v15, v16, v15
	v_add_f32_e32 v19, v17, v15
	v_mul_f32_e32 v20, v19, v19
	v_fmamk_f32 v16, v20, 0x3e9b6dac, v152
	v_fmaak_f32 v35, v20, v16, 0x3f2aaada
	v_cvt_f32_i32_e32 v16, v32
	v_sub_f32_e32 v17, v19, v17
	v_sub_f32_e32 v15, v15, v17
	v_mul_f32_e32 v17, v19, v20
	v_pk_mul_f32 v[22:23], v[16:17], v[34:35]
	v_ldexp_f32 v21, v19, 1
	v_fma_f32 v20, v16, s47, -v22
	v_fmac_f32_e32 v20, 0xb102e308, v16
	v_pk_add_f32 v[16:17], v[22:23], v[20:21]
	v_ldexp_f32 v15, v15, 1
	v_sub_f32_e32 v19, v17, v21
	v_sub_f32_e32 v19, v23, v19
	v_add_f32_e32 v25, v15, v19
	v_mov_b32_e32 v24, v22
	v_pk_add_f32 v[22:23], v[16:17], v[22:23] neg_lo:[0,1] neg_hi:[0,1]
	v_pk_add_f32 v[78:79], v[16:17], v[24:25]
	v_mov_b32_e32 v21, v16
	v_mov_b32_e32 v23, v79
	v_pk_add_f32 v[80:81], v[20:21], v[22:23] neg_lo:[0,1] neg_hi:[0,1]
	v_pk_add_f32 v[20:21], v[20:21], v[22:23]
	v_mov_b32_e32 v24, v25
	v_pk_add_f32 v[22:23], v[20:21], v[16:17] op_sel:[1,0] op_sel_hi:[0,1] neg_lo:[0,1] neg_hi:[0,1]
	v_pk_add_f32 v[82:83], v[78:79], v[22:23] op_sel_hi:[1,0] neg_lo:[0,1] neg_hi:[0,1]
	v_mov_b32_e32 v78, v79
	v_mov_b32_e32 v79, v21
	v_pk_mov_b32 v[22:23], v[16:17], v[22:23] op_sel:[1,0]
	v_mov_b32_e32 v25, v16
	v_pk_add_f32 v[22:23], v[78:79], v[22:23] neg_lo:[0,1] neg_hi:[0,1]
	v_mov_b32_e32 v82, v80
	v_pk_add_f32 v[16:17], v[24:25], v[22:23] neg_lo:[0,1] neg_hi:[0,1]
	v_mov_b32_e32 v81, v21
	v_pk_add_f32 v[22:23], v[82:83], v[16:17]
	s_nop 0
	v_pk_add_f32 v[24:25], v[22:23], v[22:23] op_sel:[0,1] op_sel_hi:[1,0]
	s_nop 0
	v_pk_add_f32 v[20:21], v[20:21], v[24:25] op_sel:[1,0] op_sel_hi:[0,1]
	v_mov_b32_e32 v23, v20
	v_pk_add_f32 v[78:79], v[22:23], v[80:81] neg_lo:[0,1] neg_hi:[0,1]
	v_mov_b32_e32 v17, v24
	v_sub_f32_e32 v15, v22, v78
	v_pk_add_f32 v[16:17], v[16:17], v[78:79] neg_lo:[0,1] neg_hi:[0,1]
	v_sub_f32_e32 v15, v80, v15
	v_add_f32_e32 v15, v16, v15
	v_add_f32_e32 v15, v15, v17
	v_add_f32_e32 v15, v20, v15
	v_cndmask_b32_e32 v15, v153, v15, vcc
	v_cmp_ngt_f32_e32 vcc, -1.0, v1
	v_add_u32_e32 v80, 7, v40
	v_ashrrev_i32_e32 v81, 31, v80
	v_cndmask_b32_e32 v15, v154, v15, vcc
	v_cmp_neq_f32_e32 vcc, -1.0, v1
	v_lshlrev_b64 v[78:79], 5, v[80:81]
	v_lshl_add_u64 v[16:17], s[6:7], 0, v[78:79]
	v_cndmask_b32_e32 v15, v155, v15, vcc
	v_cmp_lt_f32_e64 vcc, |v1|, s49
	v_lshl_add_u64 v[16:17], v[16:17], 0, v[2:3]
	s_lshl_b32 s6, s38, 10
	v_cndmask_b32_e32 v1, v15, v1, vcc
	v_sub_f32_e32 v19, v5, v1
	v_mov_b32_e32 v1, v77
	v_pk_add_f32 v[82:83], v[0:1], v[18:19]
	s_mov_b32 s7, s29
	v_sub_f32_e32 v32, v82, v83
	v_max_f32_e32 v4, v4, v32
	v_max_f32_e32 v82, v14, v4
	v_sub_f32_e32 v1, v6, v82
	v_mul_f32_e32 v1, 0x3fb8aa3b, v1
	v_exp_f32_e32 v14, v1
	v_mov_b32_e32 v2, v198
	v_mov_b32_e32 v1, v199
	s_waitcnt vmcnt(0) lgkmcnt(0)
	v_add_f32_e32 v1, v7, v1
	v_min_f32_e32 v3, 0, v1
	v_mul_f32_e64 v1, |v1|, s45
	v_exp_f32_e32 v1, v1
	s_nop 0
	v_add_f32_e32 v5, 1.0, v1
	v_add_f32_e32 v7, -1.0, v5
	v_sub_f32_e32 v15, v7, v5
	v_add_f32_e32 v15, 1.0, v15
	v_sub_f32_e32 v7, v1, v7
	v_add_f32_e32 v7, v7, v15
	v_frexp_mant_f32_e32 v15, v5
	v_cvt_f64_f32_e32 v[16:17], v5
	v_cmp_gt_f32_e32 vcc, s46, v15
	v_frexp_exp_i32_f64_e32 v15, v[16:17]
	s_nop 0
	v_subbrev_co_u32_e32 v15, vcc, 0, v15, vcc
	v_sub_u32_e32 v16, 0, v15
	v_ldexp_f32 v5, v5, v16
	v_ldexp_f32 v7, v7, v16
	v_add_f32_e32 v16, -1.0, v5
	v_add_f32_e32 v17, 1.0, v16
	v_sub_f32_e32 v17, v5, v17
	v_add_f32_e32 v18, v7, v17
	v_add_f32_e32 v17, 1.0, v5
	v_add_f32_e32 v19, -1.0, v17
	v_sub_f32_e32 v5, v5, v19
	v_add_f32_e32 v5, v7, v5
	v_add_f32_e32 v7, v17, v5
	v_rcp_f32_e32 v24, v7
	v_sub_f32_e32 v17, v7, v17
	v_sub_f32_e32 v5, v5, v17
	v_add_f32_e32 v17, v16, v18
	v_sub_f32_e32 v16, v17, v16
	v_mul_f32_e32 v35, v17, v24
	v_sub_f32_e32 v25, v18, v16
	v_mul_f32_e32 v18, v7, v35
	v_fma_f32 v20, v35, v7, -v18
	v_fmac_f32_e32 v20, v35, v5
	v_add_f32_e32 v16, v18, v20
	v_sub_f32_e32 v19, v17, v16
	v_pk_add_f32 v[22:23], v[16:17], v[18:19] neg_lo:[0,1] neg_hi:[0,1]
	v_mov_b32_e32 v21, v16
	v_pk_add_f32 v[16:17], v[22:23], v[20:21] neg_lo:[0,1] neg_hi:[0,1]
	v_cmp_neq_f32_e32 vcc, s48, v1
	v_add_f32_e32 v17, v25, v17
	v_add_f32_e32 v16, v16, v17
	v_add_f32_e32 v17, v19, v16
	v_mul_f32_e32 v25, v24, v17
	v_mul_f32_e32 v18, v7, v25
	v_fma_f32 v20, v25, v7, -v18
	v_fmac_f32_e32 v20, v25, v5
	v_sub_f32_e32 v5, v19, v17
	v_add_f32_e32 v5, v16, v5
	v_add_f32_e32 v16, v18, v20
	v_sub_f32_e32 v19, v17, v16
	v_pk_add_f32 v[22:23], v[16:17], v[18:19] neg_lo:[0,1] neg_hi:[0,1]
	v_mov_b32_e32 v21, v16
	v_pk_add_f32 v[16:17], v[22:23], v[20:21] neg_lo:[0,1] neg_hi:[0,1]
	v_add_f32_e32 v7, v35, v25
	v_add_f32_e32 v5, v5, v17
	v_add_f32_e32 v5, v16, v5
	v_add_f32_e32 v5, v19, v5
	v_sub_f32_e32 v16, v7, v35
	v_mul_f32_e32 v5, v24, v5
	v_sub_f32_e32 v16, v25, v16
	v_add_f32_e32 v5, v16, v5
	v_add_f32_e32 v17, v7, v5
	v_mul_f32_e32 v18, v17, v17
	v_fmamk_f32 v16, v18, 0x3e9b6dac, v152
	v_fmaak_f32 v35, v18, v16, 0x3f2aaada
	v_cvt_f32_i32_e32 v16, v15
	v_sub_f32_e32 v7, v17, v7
	v_ldexp_f32 v19, v17, 1
	v_mul_f32_e32 v17, v17, v18
	v_pk_mul_f32 v[20:21], v[16:17], v[34:35]
	v_sub_f32_e32 v5, v5, v7
	v_fma_f32 v18, v16, s47, -v20
	v_fmac_f32_e32 v18, 0xb102e308, v16
	v_pk_add_f32 v[16:17], v[20:21], v[18:19]
	v_ldexp_f32 v5, v5, 1
	v_sub_f32_e32 v7, v17, v19
	v_sub_f32_e32 v7, v21, v7
	v_add_f32_e32 v23, v5, v7
	v_mov_b32_e32 v22, v20
	v_pk_add_f32 v[20:21], v[16:17], v[20:21] neg_lo:[0,1] neg_hi:[0,1]
	v_pk_add_f32 v[24:25], v[16:17], v[22:23]
	v_mov_b32_e32 v19, v16
	v_mov_b32_e32 v21, v25
	v_pk_add_f32 v[84:85], v[18:19], v[20:21] neg_lo:[0,1] neg_hi:[0,1]
	v_pk_add_f32 v[18:19], v[18:19], v[20:21]
	v_mov_b32_e32 v22, v23
	v_pk_add_f32 v[20:21], v[18:19], v[16:17] op_sel:[1,0] op_sel_hi:[0,1] neg_lo:[0,1] neg_hi:[0,1]
	v_pk_add_f32 v[86:87], v[24:25], v[20:21] op_sel_hi:[1,0] neg_lo:[0,1] neg_hi:[0,1]
	v_mov_b32_e32 v24, v25
	v_mov_b32_e32 v25, v19
	v_pk_mov_b32 v[20:21], v[16:17], v[20:21] op_sel:[1,0]
	v_mov_b32_e32 v23, v16
	v_pk_add_f32 v[20:21], v[24:25], v[20:21] neg_lo:[0,1] neg_hi:[0,1]
	v_mov_b32_e32 v86, v84
	v_pk_add_f32 v[16:17], v[22:23], v[20:21] neg_lo:[0,1] neg_hi:[0,1]
	v_mov_b32_e32 v85, v19
	v_pk_add_f32 v[20:21], v[86:87], v[16:17]
	s_nop 0
	v_pk_add_f32 v[22:23], v[20:21], v[20:21] op_sel:[0,1] op_sel_hi:[1,0]
	s_nop 0
	v_pk_add_f32 v[18:19], v[18:19], v[22:23] op_sel:[1,0] op_sel_hi:[0,1]
	v_mov_b32_e32 v21, v18
	v_pk_add_f32 v[24:25], v[20:21], v[84:85] neg_lo:[0,1] neg_hi:[0,1]
	v_mov_b32_e32 v17, v22
	v_sub_f32_e32 v5, v20, v24
	v_pk_add_f32 v[16:17], v[16:17], v[24:25] neg_lo:[0,1] neg_hi:[0,1]
	v_sub_f32_e32 v5, v84, v5
	v_add_f32_e32 v5, v16, v5
	v_add_f32_e32 v5, v5, v17
	v_add_f32_e32 v5, v18, v5
	v_cndmask_b32_e32 v5, v153, v5, vcc
	v_cmp_ngt_f32_e32 vcc, -1.0, v1
	s_nop 1
	v_cndmask_b32_e32 v5, v154, v5, vcc
	v_cmp_neq_f32_e32 vcc, -1.0, v1
	s_nop 1
	v_cndmask_b32_e32 v5, v155, v5, vcc
	v_cmp_lt_f32_e64 vcc, |v1|, s49
	s_nop 1
	v_cndmask_b32_e32 v1, v5, v1, vcc
	v_sub_f32_e32 v3, v3, v1
	v_mov_b32_e32 v1, v83
	v_pk_add_f32 v[84:85], v[0:1], v[2:3]
	v_and_b32_e32 v2, 0xffffffc0, v36
	v_sub_f32_e32 v87, v84, v85
	v_max3_f32 v35, v6, v4, v87
	v_sub_f32_e32 v0, v6, v35
	v_mul_f32_e32 v0, 0x3fb8aa3b, v0
	v_exp_f32_e32 v86, v0
	v_sub_f32_e32 v0, v26, v35
	v_mul_f32_e32 v0, 0x3fb8aa3b, v0
	v_exp_f32_e32 v22, v0
	v_sub_f32_e32 v0, v27, v35
	v_mul_f32_e32 v0, 0x3fb8aa3b, v0
	v_exp_f32_e32 v23, v0
	v_sub_f32_e32 v0, v28, v35
	v_mul_f32_e32 v0, 0x3fb8aa3b, v0
	v_exp_f32_e32 v20, v0
	v_sub_f32_e32 v0, v29, v35
	v_mul_f32_e32 v0, 0x3fb8aa3b, v0
	v_exp_f32_e32 v21, v0
	v_sub_f32_e32 v0, v30, v35
	v_mul_f32_e32 v0, 0x3fb8aa3b, v0
	v_exp_f32_e32 v18, v0
	v_sub_f32_e32 v0, v31, v35
	v_mul_f32_e32 v0, 0x3fb8aa3b, v0
	v_exp_f32_e32 v19, v0
	v_sub_f32_e32 v0, v32, v35
	v_mul_f32_e32 v0, 0x3fb8aa3b, v0
	v_exp_f32_e32 v16, v0
	v_sub_f32_e32 v0, v87, v35
	v_mul_f32_e32 v0, 0x3fb8aa3b, v0
	v_exp_f32_e32 v17, v0
	v_bfe_u32 v0, v36, 3, 3
	v_add_u32_e32 v0, v40, v0
	v_ashrrev_i32_e32 v1, 31, v0
	v_lshlrev_b64 v[0:1], 12, v[0:1]
	v_lshl_add_u64 v[0:1], s[24:25], 0, v[0:1]
	v_ashrrev_i32_e32 v3, 31, v2
	v_lshl_add_u64 v[0:1], v[0:1], 0, s[6:7]
	v_lshlrev_b64 v[2:3], 1, v[2:3]
	v_lshl_add_u64 v[0:1], v[0:1], 0, v[2:3]
	flat_load_dwordx4 v[92:95], v[0:1]
	v_add_u32_e32 v4, v40, v90
	v_ashrrev_i32_e32 v5, 31, v4
	v_lshlrev_b64 v[4:5], 12, v[4:5]
	v_lshl_add_u64 v[4:5], s[20:21], 0, v[4:5]
	v_lshl_add_u64 v[4:5], v[4:5], 0, s[6:7]
	v_lshl_add_u64 v[4:5], v[4:5], 0, v[2:3]
	s_lshl_b64 s[6:7], s[34:35], 11
	s_add_u32 s36, s14, s6
	s_addc_u32 s37, s15, s7
	v_pk_mul_f32 v[16:17], v[16:17], s[30:31] op_sel_hi:[1,0]
	s_add_u32 s6, s8, s6
	s_addc_u32 s7, s9, s7
	v_and_b32_e32 v84, 63, v36
	global_load_dwordx4 v[102:105], v[4:5], off
	global_load_dwordx4 v[106:109], v[0:1], off offset:16
	global_load_dwordx4 v[110:113], v[4:5], off offset:16
	global_load_dwordx4 v[114:117], v[0:1], off offset:32
	global_load_dwordx4 v[118:121], v[4:5], off offset:32
	global_load_dwordx4 v[122:125], v[0:1], off offset:48
	global_load_dwordx4 v[126:129], v[4:5], off offset:48
	global_load_dwordx4 v[130:133], v[0:1], off offset:64
	global_load_dwordx4 v[134:137], v[4:5], off offset:64
	global_load_dwordx4 v[138:141], v[0:1], off offset:80
	global_load_dwordx4 v[142:145], v[4:5], off offset:80
	global_load_dwordx4 v[158:161], v[0:1], off offset:96
	global_load_dwordx4 v[162:165], v[4:5], off offset:96
	s_waitcnt vmcnt(0) lgkmcnt(0)
	v_lshlrev_b32_e32 v2, 16, v92
	v_and_b32_e32 v3, 0xffff0000, v92
	v_lshlrev_b32_e32 v6, 16, v93
	v_and_b32_e32 v7, 0xffff0000, v93
	v_lshlrev_b32_e32 v15, 16, v94
	v_and_b32_e32 v24, 0xffff0000, v94
	v_lshlrev_b32_e32 v25, 16, v95
	v_and_b32_e32 v37, 0xffff0000, v95
	v_mov_b64_e32 v[92:93], v[102:103]
	v_mov_b64_e32 v[94:95], v[104:105]
	s_waitcnt vmcnt(0) lgkmcnt(0)
	v_lshlrev_b32_e32 v88, 16, v92
	v_and_b32_e32 v89, 0xffff0000, v92
	v_fma_f32 v2, v2, v88, 0
	v_lshlrev_b32_e32 v91, 16, v93
	v_fmac_f32_e32 v2, v3, v89
	v_and_b32_e32 v92, 0xffff0000, v93
	v_fmac_f32_e32 v2, v6, v91
	v_lshlrev_b32_e32 v93, 16, v94
	v_fmac_f32_e32 v2, v7, v92
	v_and_b32_e32 v94, 0xffff0000, v94
	v_fmac_f32_e32 v2, v15, v93
	v_lshlrev_b32_e32 v96, 16, v95
	v_fmac_f32_e32 v2, v24, v94
	v_and_b32_e32 v95, 0xffff0000, v95
	v_fmac_f32_e32 v2, v25, v96
	v_fmac_f32_e32 v2, v37, v95
	v_mov_b64_e32 v[92:93], v[106:107]
	v_mov_b64_e32 v[94:95], v[108:109]
	s_waitcnt vmcnt(0) lgkmcnt(0)
	v_lshlrev_b32_e32 v3, 16, v92
	v_and_b32_e32 v6, 0xffff0000, v92
	v_lshlrev_b32_e32 v7, 16, v93
	v_and_b32_e32 v15, 0xffff0000, v93
	v_lshlrev_b32_e32 v24, 16, v94
	v_and_b32_e32 v25, 0xffff0000, v94
	v_lshlrev_b32_e32 v37, 16, v95
	v_and_b32_e32 v88, 0xffff0000, v95
	v_mov_b64_e32 v[92:93], v[110:111]
	v_mov_b64_e32 v[94:95], v[112:113]
	s_waitcnt vmcnt(0) lgkmcnt(0)
	v_lshlrev_b32_e32 v89, 16, v92
	v_and_b32_e32 v91, 0xffff0000, v92
	v_fmac_f32_e32 v2, v3, v89
	v_lshlrev_b32_e32 v92, 16, v93
	v_fmac_f32_e32 v2, v6, v91
	v_and_b32_e32 v93, 0xffff0000, v93
	v_fmac_f32_e32 v2, v7, v92
	v_lshlrev_b32_e32 v96, 16, v94
	v_fmac_f32_e32 v2, v15, v93
	v_and_b32_e32 v94, 0xffff0000, v94
	v_fmac_f32_e32 v2, v24, v96
	v_lshlrev_b32_e32 v97, 16, v95
	v_fmac_f32_e32 v2, v25, v94
	v_and_b32_e32 v95, 0xffff0000, v95
	v_fmac_f32_e32 v2, v37, v97
	v_fmac_f32_e32 v2, v88, v95
	v_mov_b64_e32 v[92:93], v[114:115]
	v_mov_b64_e32 v[94:95], v[116:117]
	s_waitcnt vmcnt(0) lgkmcnt(0)
	v_lshlrev_b32_e32 v3, 16, v92
	v_and_b32_e32 v6, 0xffff0000, v92
	v_lshlrev_b32_e32 v7, 16, v93
	v_and_b32_e32 v15, 0xffff0000, v93
	v_lshlrev_b32_e32 v24, 16, v94
	v_and_b32_e32 v25, 0xffff0000, v94
	v_lshlrev_b32_e32 v37, 16, v95
	v_and_b32_e32 v88, 0xffff0000, v95
	v_mov_b64_e32 v[92:93], v[118:119]
	v_mov_b64_e32 v[94:95], v[120:121]
	s_waitcnt vmcnt(0) lgkmcnt(0)
	v_lshlrev_b32_e32 v89, 16, v92
	v_and_b32_e32 v91, 0xffff0000, v92
	v_fmac_f32_e32 v2, v3, v89
	v_lshlrev_b32_e32 v92, 16, v93
	v_fmac_f32_e32 v2, v6, v91
	v_and_b32_e32 v93, 0xffff0000, v93
	v_fmac_f32_e32 v2, v7, v92
	v_lshlrev_b32_e32 v96, 16, v94
	v_fmac_f32_e32 v2, v15, v93
	v_and_b32_e32 v94, 0xffff0000, v94
	v_fmac_f32_e32 v2, v24, v96
	v_lshlrev_b32_e32 v97, 16, v95
	v_fmac_f32_e32 v2, v25, v94
	v_and_b32_e32 v95, 0xffff0000, v95
	v_fmac_f32_e32 v2, v37, v97
	v_fmac_f32_e32 v2, v88, v95
	v_mov_b64_e32 v[92:93], v[122:123]
	v_mov_b64_e32 v[94:95], v[124:125]
	s_waitcnt vmcnt(0) lgkmcnt(0)
	v_lshlrev_b32_e32 v3, 16, v92
	v_and_b32_e32 v6, 0xffff0000, v92
	v_lshlrev_b32_e32 v7, 16, v93
	v_and_b32_e32 v15, 0xffff0000, v93
	v_lshlrev_b32_e32 v24, 16, v94
	v_and_b32_e32 v25, 0xffff0000, v94
	v_lshlrev_b32_e32 v37, 16, v95
	v_and_b32_e32 v88, 0xffff0000, v95
	v_mov_b64_e32 v[92:93], v[126:127]
	v_mov_b64_e32 v[94:95], v[128:129]
	s_waitcnt vmcnt(0) lgkmcnt(0)
	v_lshlrev_b32_e32 v89, 16, v92
	v_and_b32_e32 v91, 0xffff0000, v92
	v_fmac_f32_e32 v2, v3, v89
	v_lshlrev_b32_e32 v92, 16, v93
	v_fmac_f32_e32 v2, v6, v91
	v_and_b32_e32 v93, 0xffff0000, v93
	v_fmac_f32_e32 v2, v7, v92
	v_lshlrev_b32_e32 v96, 16, v94
	v_fmac_f32_e32 v2, v15, v93
	v_and_b32_e32 v94, 0xffff0000, v94
	v_fmac_f32_e32 v2, v24, v96
	v_lshlrev_b32_e32 v97, 16, v95
	v_fmac_f32_e32 v2, v25, v94
	v_and_b32_e32 v95, 0xffff0000, v95
	v_fmac_f32_e32 v2, v37, v97
	v_fmac_f32_e32 v2, v88, v95
	v_mov_b64_e32 v[92:93], v[130:131]
	v_mov_b64_e32 v[94:95], v[132:133]
	s_waitcnt vmcnt(0) lgkmcnt(0)
	v_lshlrev_b32_e32 v3, 16, v92
	v_and_b32_e32 v6, 0xffff0000, v92
	v_lshlrev_b32_e32 v7, 16, v93
	v_and_b32_e32 v15, 0xffff0000, v93
	v_lshlrev_b32_e32 v24, 16, v94
	v_and_b32_e32 v25, 0xffff0000, v94
	v_lshlrev_b32_e32 v37, 16, v95
	v_and_b32_e32 v88, 0xffff0000, v95
	v_mov_b64_e32 v[92:93], v[134:135]
	v_mov_b64_e32 v[94:95], v[136:137]
	s_waitcnt vmcnt(0) lgkmcnt(0)
	v_lshlrev_b32_e32 v89, 16, v92
	v_and_b32_e32 v91, 0xffff0000, v92
	v_fmac_f32_e32 v2, v3, v89
	v_lshlrev_b32_e32 v92, 16, v93
	v_fmac_f32_e32 v2, v6, v91
	v_and_b32_e32 v93, 0xffff0000, v93
	v_fmac_f32_e32 v2, v7, v92
	v_lshlrev_b32_e32 v96, 16, v94
	v_fmac_f32_e32 v2, v15, v93
	v_and_b32_e32 v94, 0xffff0000, v94
	v_fmac_f32_e32 v2, v24, v96
	v_lshlrev_b32_e32 v97, 16, v95
	v_fmac_f32_e32 v2, v25, v94
	v_and_b32_e32 v95, 0xffff0000, v95
	v_fmac_f32_e32 v2, v37, v97
	v_fmac_f32_e32 v2, v88, v95
	v_mov_b64_e32 v[92:93], v[138:139]
	v_mov_b64_e32 v[94:95], v[140:141]
	s_waitcnt vmcnt(0) lgkmcnt(0)
	v_lshlrev_b32_e32 v3, 16, v92
	v_and_b32_e32 v6, 0xffff0000, v92
	v_lshlrev_b32_e32 v7, 16, v93
	v_and_b32_e32 v15, 0xffff0000, v93
	v_lshlrev_b32_e32 v24, 16, v94
	v_and_b32_e32 v25, 0xffff0000, v94
	v_lshlrev_b32_e32 v37, 16, v95
	v_and_b32_e32 v88, 0xffff0000, v95
	v_mov_b64_e32 v[92:93], v[142:143]
	v_mov_b64_e32 v[94:95], v[144:145]
	s_waitcnt vmcnt(0) lgkmcnt(0)
	v_lshlrev_b32_e32 v89, 16, v92
	v_and_b32_e32 v91, 0xffff0000, v92
	v_fmac_f32_e32 v2, v3, v89
	v_lshlrev_b32_e32 v92, 16, v93
	v_fmac_f32_e32 v2, v6, v91
	v_and_b32_e32 v93, 0xffff0000, v93
	v_fmac_f32_e32 v2, v7, v92
	v_lshlrev_b32_e32 v96, 16, v94
	v_fmac_f32_e32 v2, v15, v93
	v_and_b32_e32 v94, 0xffff0000, v94
	v_fmac_f32_e32 v2, v24, v96
	v_lshlrev_b32_e32 v97, 16, v95
	v_fmac_f32_e32 v2, v25, v94
	v_and_b32_e32 v95, 0xffff0000, v95
	v_fmac_f32_e32 v2, v37, v97
	v_fmac_f32_e32 v2, v88, v95
	v_mov_b64_e32 v[92:93], v[158:159]
	v_mov_b64_e32 v[94:95], v[160:161]
	v_mov_b64_e32 v[96:97], v[162:163]
	v_mov_b64_e32 v[98:99], v[164:165]
	s_waitcnt vmcnt(0) lgkmcnt(0)
	v_lshlrev_b32_e32 v3, 16, v92
	v_lshlrev_b32_e32 v24, 16, v96
	v_and_b32_e32 v6, 0xffff0000, v92
	v_and_b32_e32 v25, 0xffff0000, v96
	v_fmac_f32_e32 v2, v3, v24
	v_lshlrev_b32_e32 v7, 16, v93
	v_lshlrev_b32_e32 v37, 16, v97
	v_fmac_f32_e32 v2, v6, v25
	v_and_b32_e32 v15, 0xffff0000, v93
	v_and_b32_e32 v88, 0xffff0000, v97
	v_fmac_f32_e32 v2, v7, v37
	v_and_b32_e32 v6, 0xffff0000, v94
	v_lshlrev_b32_e32 v7, 16, v94
	v_and_b32_e32 v24, 0xffff0000, v98
	v_lshlrev_b32_e32 v25, 16, v98
	v_fmac_f32_e32 v2, v15, v88
	v_pk_mul_f32 v[6:7], v[6:7], v[24:25]
	v_lshlrev_b32_e32 v3, 16, v95
	v_add_f32_e32 v2, v7, v2
	v_add_f32_e32 v15, v6, v2
	v_and_b32_e32 v2, 0xffff0000, v95
	v_and_b32_e32 v6, 0xffff0000, v99
	v_lshlrev_b32_e32 v7, 16, v99
	v_pk_mul_f32 v[2:3], v[2:3], v[6:7]
	v_ashrrev_i32_e32 v37, 31, v36
	v_add_f32_e32 v3, v3, v15
	v_add_f32_e32 v15, v2, v3
	flat_load_dwordx4 v[0:3], v[0:1] offset:112
	s_nop 0
	flat_load_dwordx4 v[4:7], v[4:5] offset:112
	s_waitcnt vmcnt(0) lgkmcnt(0)
	v_and_b32_e32 v24, 0xffff0000, v0
	v_lshlrev_b32_e32 v25, 16, v0
	v_and_b32_e32 v88, 0xffff0000, v4
	v_lshlrev_b32_e32 v89, 16, v4
	v_pk_mul_f32 v[24:25], v[24:25], v[88:89]
	v_and_b32_e32 v4, 0xffff0000, v5
	v_add_f32_e32 v0, v25, v15
	v_add_f32_e32 v15, v24, v0
	v_and_b32_e32 v0, 0xffff0000, v1
	v_lshlrev_b32_e32 v1, 16, v1
	v_lshlrev_b32_e32 v5, 16, v5
	v_pk_mul_f32 v[0:1], v[0:1], v[4:5]
	v_and_b32_e32 v4, 0xffff0000, v6
	v_add_f32_e32 v1, v1, v15
	v_add_f32_e32 v15, v0, v1
	v_and_b32_e32 v0, 0xffff0000, v2
	v_lshlrev_b32_e32 v1, 16, v2
	v_lshlrev_b32_e32 v5, 16, v6
	v_pk_mul_f32 v[0:1], v[0:1], v[4:5]
	v_and_b32_e32 v2, 0xffff0000, v7
	v_add_f32_e32 v1, v1, v15
	v_add_f32_e32 v4, v0, v1
	v_and_b32_e32 v0, 0xffff0000, v3
	v_lshlrev_b32_e32 v1, 16, v3
	v_lshlrev_b32_e32 v3, 16, v7
	v_pk_mul_f32 v[0:1], v[0:1], v[2:3]
	v_lshlrev_b64 v[24:25], 2, v[36:37]
	v_add_f32_e32 v1, v1, v4
	v_add_f32_e32 v0, v0, v1
	v_lshl_add_u32 v1, v36, 2, 0
	v_add_u32_e32 v91, 0x18000, v1
	ds_write_b32 v91, v0
	v_lshl_add_u64 v[0:1], s[36:37], 0, v[24:25]
	flat_load_dword v92, v[0:1]
	v_lshl_add_u64 v[88:89], v[36:37], 0, s[28:29]
	v_lshlrev_b64 v[0:1], 11, v[40:41]
	v_lshl_add_u64 v[0:1], v[0:1], 0, v[88:89]
	v_lshlrev_b64 v[0:1], 1, v[0:1]
	v_mov_b32_e32 v166, v0
	global_load_ushort v170, v166, s[24:25]
	global_load_ushort v178, v166, s[20:21]
	v_add_u32_e32 v166, 0x1000, v166
	global_load_ushort v171, v166, s[24:25]
	global_load_ushort v179, v166, s[20:21]
	v_add_u32_e32 v166, 0x1000, v166
	global_load_ushort v172, v166, s[24:25]
	global_load_ushort v180, v166, s[20:21]
	v_add_u32_e32 v166, 0x1000, v166
	global_load_ushort v173, v166, s[24:25]
	global_load_ushort v181, v166, s[20:21]
	v_add_u32_e32 v166, 0x1000, v166
	global_load_ushort v174, v166, s[24:25]
	global_load_ushort v182, v166, s[20:21]
	v_add_u32_e32 v166, 0x1000, v166
	global_load_ushort v175, v166, s[24:25]
	global_load_ushort v183, v166, s[20:21]
	v_add_u32_e32 v166, 0x1000, v166
	global_load_ushort v176, v166, s[24:25]
	global_load_ushort v184, v166, s[20:21]
	v_add_u32_e32 v166, 0x1000, v166
	global_load_ushort v177, v166, s[24:25]
	global_load_ushort v185, v166, s[20:21]
	v_lshl_add_u64 v[2:3], s[24:25], 0, v[0:1]
	v_lshl_add_u64 v[4:5], s[20:21], 0, v[0:1]
	v_lshlrev_b64 v[0:1], 11, v[44:45]
	v_lshl_add_u64 v[0:1], v[0:1], 0, v[88:89]
	v_lshlrev_b64 v[6:7], 1, v[0:1]
	v_lshl_add_u64 v[0:1], s[24:25], 0, v[6:7]
	s_waitcnt vmcnt(0)
	v_mov_b32_e32 v2, v170
	s_nop 0
	v_mov_b32_e32 v0, v171
	s_waitcnt vmcnt(0) lgkmcnt(0)
	v_lshlrev_b32_e32 v1, 16, v0
	v_lshlrev_b32_e32 v0, 16, v2
	v_lshl_add_u64 v[2:3], s[20:21], 0, v[6:7]
	v_mov_b32_e32 v4, v178
	s_nop 0
	v_mov_b32_e32 v2, v179
	v_pk_mul_f32 v[6:7], v[22:23], s[30:31] op_sel_hi:[1,0]
	v_pk_mul_f32 v[0:1], v[8:9], v[0:1]
	s_waitcnt vmcnt(0) lgkmcnt(0)
	v_lshlrev_b32_e32 v3, 16, v2
	v_lshlrev_b32_e32 v2, 16, v4
	v_pk_mul_f32 v[8:9], v[6:7], v[2:3]
	s_nop 0
	v_add_f32_e32 v2, 0, v8
	v_add_f32_e32 v15, v9, v2
	v_lshlrev_b64 v[2:3], 11, v[48:49]
	v_lshl_add_u64 v[2:3], v[2:3], 0, v[88:89]
	v_lshlrev_b64 v[2:3], 1, v[2:3]
	v_lshl_add_u64 v[4:5], s[24:25], 0, v[2:3]
	v_lshl_add_u64 v[6:7], s[20:21], 0, v[2:3]
	v_lshlrev_b64 v[2:3], 11, v[56:57]
	v_lshl_add_u64 v[2:3], v[2:3], 0, v[88:89]
	v_lshlrev_b64 v[22:23], 1, v[2:3]
	v_lshl_add_u64 v[2:3], s[24:25], 0, v[22:23]
	v_mov_b32_e32 v4, v172
	s_nop 0
	v_mov_b32_e32 v2, v173
	s_waitcnt vmcnt(0) lgkmcnt(0)
	v_lshlrev_b32_e32 v3, 16, v2
	v_lshlrev_b32_e32 v2, 16, v4
	v_lshl_add_u64 v[4:5], s[20:21], 0, v[22:23]
	v_mov_b32_e32 v6, v180
	s_nop 0
	v_mov_b32_e32 v4, v181
	v_pk_mul_f32 v[2:3], v[10:11], v[2:3]
	v_pk_mul_f32 v[10:11], v[20:21], s[30:31] op_sel_hi:[1,0]
	s_waitcnt vmcnt(0) lgkmcnt(0)
	v_lshlrev_b32_e32 v5, 16, v4
	v_lshlrev_b32_e32 v4, 16, v6
	v_pk_mul_f32 v[10:11], v[10:11], v[4:5]
	s_nop 0
	v_add_f32_e32 v4, v10, v15
	v_add_f32_e32 v15, v11, v4
	v_lshlrev_b64 v[4:5], 11, v[62:63]
	v_lshl_add_u64 v[4:5], v[4:5], 0, v[88:89]
	v_lshlrev_b64 v[4:5], 1, v[4:5]
	v_lshl_add_u64 v[6:7], s[24:25], 0, v[4:5]
	v_lshl_add_u64 v[20:21], s[20:21], 0, v[4:5]
	v_lshlrev_b64 v[4:5], 11, v[70:71]
	v_lshl_add_u64 v[4:5], v[4:5], 0, v[88:89]
	v_lshlrev_b64 v[22:23], 1, v[4:5]
	v_lshl_add_u64 v[4:5], s[24:25], 0, v[22:23]
	v_mov_b32_e32 v6, v174
	s_nop 0
	v_mov_b32_e32 v4, v175
	s_waitcnt vmcnt(0) lgkmcnt(0)
	v_lshlrev_b32_e32 v5, 16, v4
	v_lshlrev_b32_e32 v4, 16, v6
	v_lshl_add_u64 v[6:7], s[20:21], 0, v[22:23]
	v_pk_mul_f32 v[4:5], v[12:13], v[4:5]
	v_pk_mul_f32 v[12:13], v[18:19], s[30:31] op_sel_hi:[1,0]
	v_mov_b32_e32 v18, v182
	s_nop 0
	v_mov_b32_e32 v6, v183
	s_waitcnt vmcnt(0) lgkmcnt(0)
	v_lshlrev_b32_e32 v7, 16, v6
	v_lshlrev_b32_e32 v6, 16, v18
	v_pk_mul_f32 v[12:13], v[12:13], v[6:7]
	s_nop 0
	v_add_f32_e32 v6, v12, v15
	v_add_f32_e32 v93, v13, v6
	v_lshlrev_b64 v[6:7], 11, v[74:75]
	v_lshl_add_u64 v[6:7], v[6:7], 0, v[88:89]
	v_lshlrev_b64 v[6:7], 1, v[6:7]
	v_lshl_add_u64 v[18:19], s[24:25], 0, v[6:7]
	v_lshl_add_u64 v[20:21], s[20:21], 0, v[6:7]
	v_lshlrev_b64 v[6:7], 11, v[80:81]
	v_lshl_add_u64 v[6:7], v[6:7], 0, v[88:89]
	v_lshlrev_b64 v[22:23], 1, v[6:7]
	v_lshl_add_u64 v[6:7], s[24:25], 0, v[22:23]
	v_mov_b32_e32 v15, v176
	s_nop 0
	v_mov_b32_e32 v6, v177
	s_waitcnt vmcnt(0) lgkmcnt(0)
	v_lshlrev_b32_e32 v7, 16, v6
	v_lshlrev_b32_e32 v6, 16, v15
	v_mov_b32_e32 v15, v86
	v_pk_mul_f32 v[6:7], v[14:15], v[6:7]
	v_lshl_add_u64 v[14:15], s[20:21], 0, v[22:23]
	v_mov_b32_e32 v18, v184
	s_nop 0
	v_mov_b32_e32 v14, v185
	s_waitcnt vmcnt(0) lgkmcnt(0)
	v_lshlrev_b32_e32 v15, 16, v14
	v_lshlrev_b32_e32 v14, 16, v18
	v_pk_mul_f32 v[14:15], v[16:17], v[14:15]
	v_lshl_add_u32 v17, v36, 5, 0
	v_add_f32_e32 v16, v14, v93
	ds_write_b128 v17, v[0:3]
	ds_write_b128 v17, v[4:7] offset:16
	ds_write_b128 v17, v[8:11] offset:16384
	ds_write_b128 v17, v[12:15] offset:16400
	v_lshl_add_u64 v[8:9], s[6:7], 0, v[24:25]
	s_mov_b32 s6, 0x26960000
	v_add_f32_e32 v16, v15, v16
	v_add_co_u32_e32 v8, vcc, s6, v8
	v_fmac_f32_e32 v16, v92, v86
	s_nop 0
	v_addc_co_u32_e32 v9, vcc, 0, v9, vcc
	flat_store_dword v[8:9], v16
	v_mul_f32_e32 v9, v92, v0
	ds_bpermute_b32 v9, v146, v9
	v_cmp_eq_u32_e64 s[6:7], 0, v84
	v_ashrrev_i32_e32 v8, 1, v36
	s_waitcnt lgkmcnt(0)
	v_fmac_f32_e32 v9, v92, v0
	ds_bpermute_b32 v0, v147, v9
	s_waitcnt lgkmcnt(0)
	v_add_f32_e32 v0, v9, v0
	ds_bpermute_b32 v9, v148, v0
	s_waitcnt lgkmcnt(0)
	v_add_f32_e32 v0, v0, v9
	ds_bpermute_b32 v9, v149, v0
	s_waitcnt lgkmcnt(0)
	v_add_f32_e32 v0, v0, v9
	ds_bpermute_b32 v9, v150, v0
	s_waitcnt lgkmcnt(0)
	v_add_f32_e32 v0, v0, v9
	ds_bpermute_b32 v9, v151, v0
	s_and_saveexec_b64 s[36:37], s[6:7]
	s_cbranch_execz .LBB0_923
	s_waitcnt lgkmcnt(0)
	v_add_f32_e32 v0, v0, v9
	v_add_u32_e32 v9, 0, v8
	v_add_u32_e32 v9, 0x18900, v9
	ds_write_b32 v9, v0
